# address calc and LDS-DMA issue interleaved between MFMA groups in all four GEMM k-loops
# speedup vs baseline: 1.0494x; 1.0065x over previous
;     ...
;     for (int kt = 0; kt < nk; ++kt) {
;       const int buf = kt & 1;
;       if (kt + 1 < nk) {
; #pragma unroll
;         for (int i = 0; i < 4; ++i) ra[i] = *(const u32x4*)(Ag + (size_t)(i * 64) * K + (kt + 1) * 32);
; #pragma unroll
;         for (int i = 0; i < 2; ++i) rb[i] = *(const u32x4*)(Bg + (size_t)(i * 64) * K + (kt + 1) * 32);
;       }
;       const char* As = smem + buf * 24576;
;       const char* Bs = As + 16384;
;       bf16x8 bfr[4];
; #pragma unroll
;       for (int j = 0; j < 4; ++j) bfr[j] = *(const bf16x8*)(Bs + (wn * 64 + j * 16 + l15) * 64 + rsw);
;       bf16x8 afr[8];
; #pragma unroll
;       for (int i = 0; i < 8; ++i) afr[i] = *(const bf16x8*)(As + (wm * 128 + i * 16 + l15) * 64 + rsw);
;       __builtin_amdgcn_s_setprio(1);
; #pragma unroll
;       for (int i = 0; i < 8; ++i) {
; #pragma unroll
;         for (int j = 0; j < 4; ++j) acc[i][j] = __builtin_amdgcn_mfma_f32_16x16x32_bf16(bfr[j], afr[i], acc[i][j], 0, 0, 0);
;       }
;       __builtin_amdgcn_s_setprio(0);
;       if (kt + 1 < nk) {
;         char* Aw = smem + (buf ^ 1) * 24576;
;         char* Bw = Aw + 16384;
; #pragma unroll
;         for (int i = 0; i < 4; ++i) *(u32x4*)(Aw + (ldrow + i * 64) * 64 + lsw) = ra[i];
; #pragma unroll
;         for (int i = 0; i < 2; ++i) *(u32x4*)(Bw + (ldrow + i * 64) * 64 + lsw) = rb[i];
;       }
;       __syncthreads();
.LBB0_126:
	v_add_u32_e32 v146, s21, v153
	v_add3_u32 v147, v146, v150, v151
	v_add_u32_e32 v146, v146, v152
	ds_read_b128 v[176:179], v147 offset:16384
	ds_read_b128 v[180:183], v147 offset:17408
	ds_read_b128 v[184:187], v147 offset:18432
	ds_read_b128 v[188:191], v147 offset:19456
	ds_read_b128 v[192:195], v146
	ds_read_b128 v[196:199], v146 offset:1024
	ds_read_b128 v[230:233], v146 offset:2048
	ds_read_b128 v[234:237], v146 offset:3072
	ds_read_b128 v[238:241], v146 offset:4096
	ds_read_b128 v[242:245], v146 offset:5120
	ds_read_b128 v[246:249], v146 offset:6144
	ds_read_b128 v[220:223], v146 offset:7168
	s_setprio 1
	s_waitcnt lgkmcnt(7)
	v_mfma_f32_16x16x32_bf16 v[128:131], v[176:179], v[192:195], v[128:131]
	v_mfma_f32_16x16x32_bf16 v[124:127], v[180:183], v[192:195], v[124:127]
	v_mfma_f32_16x16x32_bf16 v[120:123], v[184:187], v[192:195], v[120:123]
	v_mfma_f32_16x16x32_bf16 v[116:119], v[188:191], v[192:195], v[116:119]
	v_lshl_add_u64 v[142:143], v[140:141], 0, s[2:3]
	v_add_co_u32_e32 v156, vcc, s9, v142
	v_lshl_add_u64 v[146:147], v[138:139], 0, s[2:3]
	s_add_u32 s23, s22, s20
	v_addc_co_u32_e32 v157, vcc, 0, v143, vcc
	s_waitcnt lgkmcnt(6)
	v_mfma_f32_16x16x32_bf16 v[112:115], v[176:179], v[196:199], v[112:115]
	v_mfma_f32_16x16x32_bf16 v[108:111], v[180:183], v[196:199], v[108:111]
	v_mfma_f32_16x16x32_bf16 v[104:107], v[184:187], v[196:199], v[104:107]
	v_mfma_f32_16x16x32_bf16 v[100:103], v[188:191], v[196:199], v[100:103]
	v_add_co_u32_e32 v160, vcc, s12, v142
	s_add_u32 m0, s23, 0x4000
	s_nop 0
	v_addc_co_u32_e32 v161, vcc, 0, v143, vcc
	v_add_co_u32_e32 v164, vcc, s13, v142
	s_waitcnt lgkmcnt(5)
	v_mfma_f32_16x16x32_bf16 v[96:99], v[176:179], v[230:233], v[96:99]
	v_mfma_f32_16x16x32_bf16 v[92:95], v[180:183], v[230:233], v[92:95]
	v_mfma_f32_16x16x32_bf16 v[88:91], v[184:187], v[230:233], v[88:91]
	v_mfma_f32_16x16x32_bf16 v[84:87], v[188:191], v[230:233], v[84:87]
	s_add_i32 s6, s6, 1
	s_nop 0
	v_addc_co_u32_e32 v165, vcc, 0, v143, vcc
	v_add_co_u32_e32 v168, vcc, s14, v142
	s_nop 1
	s_waitcnt lgkmcnt(4)
	v_mfma_f32_16x16x32_bf16 v[80:83], v[176:179], v[234:237], v[80:83]
	v_mfma_f32_16x16x32_bf16 v[76:79], v[180:183], v[234:237], v[76:79]
	v_mfma_f32_16x16x32_bf16 v[72:75], v[184:187], v[234:237], v[72:75]
	v_mfma_f32_16x16x32_bf16 v[68:71], v[188:191], v[234:237], v[68:71]
	v_addc_co_u32_e32 v169, vcc, 0, v143, vcc
	global_load_lds_dwordx4 v[146:147], off
	v_add_co_u32_e32 v146, vcc, s11, v146
	s_mov_b32 m0, s23
	s_nop 0
	s_waitcnt lgkmcnt(3)
	v_mfma_f32_16x16x32_bf16 v[64:67], v[176:179], v[238:241], v[64:67]
	v_mfma_f32_16x16x32_bf16 v[60:63], v[180:183], v[238:241], v[60:63]
	v_mfma_f32_16x16x32_bf16 v[56:59], v[184:187], v[238:241], v[56:59]
	v_mfma_f32_16x16x32_bf16 v[52:55], v[188:191], v[238:241], v[52:55]
	v_addc_co_u32_e32 v147, vcc, 0, v147, vcc
	global_load_lds_dwordx4 v[156:157], off
	s_add_u32 m0, s23, 0x1000
	s_nop 0
	global_load_lds_dwordx4 v[160:161], off
	s_waitcnt lgkmcnt(2)
	v_mfma_f32_16x16x32_bf16 v[48:51], v[176:179], v[242:245], v[48:51]
	v_mfma_f32_16x16x32_bf16 v[44:47], v[180:183], v[242:245], v[44:47]
	v_mfma_f32_16x16x32_bf16 v[40:43], v[184:187], v[242:245], v[40:43]
	v_mfma_f32_16x16x32_bf16 v[36:39], v[188:191], v[242:245], v[36:39]
	s_add_u32 m0, s23, 0x2000
	s_nop 0
	global_load_lds_dwordx4 v[164:165], off
	s_add_u32 m0, s23, 0x3000
	s_nop 0
	s_waitcnt lgkmcnt(1)
	v_mfma_f32_16x16x32_bf16 v[32:35], v[176:179], v[246:249], v[32:35]
	v_mfma_f32_16x16x32_bf16 v[28:31], v[180:183], v[246:249], v[28:31]
	v_mfma_f32_16x16x32_bf16 v[24:27], v[184:187], v[246:249], v[24:27]
	v_mfma_f32_16x16x32_bf16 v[20:23], v[188:191], v[246:249], v[20:23]
	global_load_lds_dwordx4 v[168:169], off
	s_add_u32 m0, s23, 0x5000
	s_nop 0
	global_load_lds_dwordx4 v[146:147], off
	s_waitcnt lgkmcnt(0)
	v_mfma_f32_16x16x32_bf16 v[16:19], v[176:179], v[220:223], v[16:19]
	v_mfma_f32_16x16x32_bf16 v[12:15], v[180:183], v[220:223], v[12:15]
	v_mfma_f32_16x16x32_bf16 v[8:11], v[184:187], v[220:223], v[8:11]
	v_mfma_f32_16x16x32_bf16 v[4:7], v[188:191], v[220:223], v[4:7]
	s_setprio 0
	s_add_u32 s2, s2, 64
	s_addc_u32 s3, s3, 0
	s_add_u32 s21, s21, 0x6000
	s_cmp_eq_u32 s21, 0x12000
	s_cselect_b32 s21, 0, s21
	s_add_u32 s22, s22, 0x6000
	s_cmp_eq_u32 s22, 0x12000
	s_cselect_b32 s22, 0, s22
	s_cmpk_eq_i32 s2, 0x1040
	s_waitcnt vmcnt(6)
	s_barrier
; DEVI u32 pack2(float a, float b) { return f2bf(a) | (f2bf(b) << 16); }
;     ...
;       const char* As = smem + buf * 24576;
;       const char* Bs = As + 16384;
;       bf16x8 bfr[4];
; #pragma unroll
;       for (int j = 0; j < 4; ++j) bfr[j] = *(const bf16x8*)(Bs + (wn * 64 + j * 16 + l15) * 64 + rsw);
;       bf16x8 afr[8];
; #pragma unroll
;       for (int i = 0; i < 8; ++i) afr[i] = *(const bf16x8*)(As + (wm * 128 + i * 16 + l15) * 64 + rsw);
;       __builtin_amdgcn_s_setprio(1);
; #pragma unroll
;       for (int i = 0; i < 8; ++i) {
; #pragma unroll
;         for (int j = 0; j < 4; ++j) acc[i][j] = __builtin_amdgcn_mfma_f32_16x16x32_bf16(bfr[j], afr[i], acc[i][j], 0, 0, 0);
;       }
;       __builtin_amdgcn_s_setprio(0);
;       if (kt + 1 < nk) {
;         char* Aw = smem + (buf ^ 1) * 24576;
;         char* Bw = Aw + 16384;
; #pragma unroll
;         for (int i = 0; i < 4; ++i) *(u32x4*)(Aw + (ldrow + i * 64) * 64 + lsw) = ra[i];
; #pragma unroll
;         for (int i = 0; i < 2; ++i) *(u32x4*)(Bw + (ldrow + i * 64) * 64 + lsw) = rb[i];
;       }
;       __syncthreads();
;     }
; #pragma unroll
;     for (int i = 0; i < 8; ++i) {
;       const int row = m0 + wm * 128 + i * 16 + l15;
; #pragma unroll
;       for (int j = 0; j < 4; ++j) {
;         const int n = n0 + wn * 64 + j * 16 + quad * 4;
;         f32x4 a = acc[i][j];
;         if (EPI == EPI_Z) {
;           u16* dst;
;           if (n0 < 1536) dst = (u16*)(p.ws + W_ZA) + (size_t)row * LZA + n;
;           else if (n0 < 4736) dst = (u16*)(p.ws + W_ZB) + (size_t)row * LZB + (n - 1536);
;           else dst = (u16*)(p.ws + W_ZC) + (size_t)row * LZC + (n - 4736);
;           *(uint2*)dst = make_uint2(pack2(a[0], a[1]), pack2(a[2], a[3]));
	s_cbranch_scc0 .LBB0_126
	v_add_u32_e32 v146, s21, v153
	v_add_u32_e32 v147, s21, v155
	v_add_u32_e32 v146, v146, v152
	ds_read_b128 v[138:141], v147 offset:16384
	ds_read_b128 v[142:145], v147 offset:17408
	ds_read_b128 v[156:159], v147 offset:18432
	ds_read_b128 v[160:163], v147 offset:19456
	ds_read_b128 v[164:167], v146
	ds_read_b128 v[168:171], v146 offset:1024
	ds_read_b128 v[172:175], v146 offset:2048
	ds_read_b128 v[176:179], v146 offset:3072
	ds_read_b128 v[180:183], v146 offset:4096
	ds_read_b128 v[184:187], v146 offset:5120
	ds_read_b128 v[188:191], v146 offset:6144
	ds_read_b128 v[192:195], v146 offset:7168
	s_setprio 1
	s_waitcnt lgkmcnt(7)
	v_mfma_f32_16x16x32_bf16 v[128:131], v[138:141], v[164:167], v[128:131]
	v_mfma_f32_16x16x32_bf16 v[124:127], v[142:145], v[164:167], v[124:127]
	v_mfma_f32_16x16x32_bf16 v[120:123], v[156:159], v[164:167], v[120:123]
	v_mfma_f32_16x16x32_bf16 v[116:119], v[160:163], v[164:167], v[116:119]
	s_waitcnt lgkmcnt(6)
	v_mfma_f32_16x16x32_bf16 v[112:115], v[138:141], v[168:171], v[112:115]
	v_mfma_f32_16x16x32_bf16 v[108:111], v[142:145], v[168:171], v[108:111]
	v_mfma_f32_16x16x32_bf16 v[104:107], v[156:159], v[168:171], v[104:107]
	v_mfma_f32_16x16x32_bf16 v[100:103], v[160:163], v[168:171], v[100:103]
	s_waitcnt lgkmcnt(5)
	v_mfma_f32_16x16x32_bf16 v[96:99], v[138:141], v[172:175], v[96:99]
	v_mfma_f32_16x16x32_bf16 v[92:95], v[142:145], v[172:175], v[92:95]
	v_mfma_f32_16x16x32_bf16 v[88:91], v[156:159], v[172:175], v[88:91]
	v_mfma_f32_16x16x32_bf16 v[84:87], v[160:163], v[172:175], v[84:87]
	s_waitcnt lgkmcnt(4)
	v_mfma_f32_16x16x32_bf16 v[80:83], v[138:141], v[176:179], v[80:83]
	v_mfma_f32_16x16x32_bf16 v[76:79], v[142:145], v[176:179], v[76:79]
	v_mfma_f32_16x16x32_bf16 v[72:75], v[156:159], v[176:179], v[72:75]
	v_mfma_f32_16x16x32_bf16 v[68:71], v[160:163], v[176:179], v[68:71]
	s_waitcnt lgkmcnt(3)
	v_mfma_f32_16x16x32_bf16 v[64:67], v[138:141], v[180:183], v[64:67]
	v_mfma_f32_16x16x32_bf16 v[60:63], v[142:145], v[180:183], v[60:63]
	v_mfma_f32_16x16x32_bf16 v[56:59], v[156:159], v[180:183], v[56:59]
	v_mfma_f32_16x16x32_bf16 v[52:55], v[160:163], v[180:183], v[52:55]
	s_waitcnt lgkmcnt(2)
	v_mfma_f32_16x16x32_bf16 v[48:51], v[138:141], v[184:187], v[48:51]
	v_mfma_f32_16x16x32_bf16 v[44:47], v[142:145], v[184:187], v[44:47]
	v_mfma_f32_16x16x32_bf16 v[40:43], v[156:159], v[184:187], v[40:43]
	v_mfma_f32_16x16x32_bf16 v[36:39], v[160:163], v[184:187], v[36:39]
	s_waitcnt lgkmcnt(1)
	v_mfma_f32_16x16x32_bf16 v[32:35], v[138:141], v[188:191], v[32:35]
	v_mfma_f32_16x16x32_bf16 v[28:31], v[142:145], v[188:191], v[28:31]
	v_mfma_f32_16x16x32_bf16 v[24:27], v[156:159], v[188:191], v[24:27]
	v_mfma_f32_16x16x32_bf16 v[20:23], v[160:163], v[188:191], v[20:23]
	s_waitcnt lgkmcnt(0)
	v_mfma_f32_16x16x32_bf16 v[16:19], v[138:141], v[192:195], v[16:19]
	v_mfma_f32_16x16x32_bf16 v[12:15], v[142:145], v[192:195], v[12:15]
	v_mfma_f32_16x16x32_bf16 v[8:11], v[156:159], v[192:195], v[8:11]
	v_mfma_f32_16x16x32_bf16 v[4:7], v[160:163], v[192:195], v[4:7]
	s_setprio 0
	s_cmpk_gt_i32 s4, 0x5ff
	v_add_u32_e32 v157, s5, v148
	v_add_u32_e32 v138, s4, v149
	s_cselect_b64 s[2:3], -1, 0
	s_cmpk_gt_u32 s4, 0x127f
	s_movk_i32 s4, 0x1400
	v_mad_i64_i32 v[142:143], s[4:5], v157, s4, 0
	s_movk_i32 s4, 0x1900
	s_nop 0
	v_mad_i64_i32 v[140:141], s[4:5], v157, s4, 0
	s_cselect_b64 s[6:7], -1, 0
	s_mov_b64 s[4:5], -1
	s_and_b64 vcc, exec, s[2:3]
	s_waitcnt vmcnt(0)
	s_barrier
	s_cbranch_vccz .LBB0_133
	v_mov_b32_e32 v139, v2
	s_and_b64 vcc, exec, s[6:7]
	s_cbranch_vccz .LBB0_130
	v_readlane_b32 s4, v251, 1
	v_readlane_b32 s5, v251, 2
	s_nop 1
	v_lshl_add_u64 v[144:145], s[4:5], 0, v[142:143]
	v_lshl_add_u64 v[144:145], v[138:139], 1, v[144:145]
	s_mov_b64 s[4:5], 0x1cfcdb00
	v_lshl_add_u64 v[146:147], v[144:145], 0, s[4:5]
	s_mov_b64 s[4:5], 0

;     ...
;     for (int kt = 0; kt < nk; ++kt) {
;       const int buf = kt & 1;
;       if (kt + 1 < nk) {
; #pragma unroll
;         for (int i = 0; i < 4; ++i) ra[i] = *(const u32x4*)(Ag + (size_t)(i * 64) * K + (kt + 1) * 32);
; #pragma unroll
;         for (int i = 0; i < 2; ++i) rb[i] = *(const u32x4*)(Bg + (size_t)(i * 64) * K + (kt + 1) * 32);
;       }
;       const char* As = smem + buf * 24576;
;       const char* Bs = As + 16384;
;       bf16x8 bfr[4];
; #pragma unroll
;       for (int j = 0; j < 4; ++j) bfr[j] = *(const bf16x8*)(Bs + (wn * 64 + j * 16 + l15) * 64 + rsw);
;       bf16x8 afr[8];
; #pragma unroll
;       for (int i = 0; i < 8; ++i) afr[i] = *(const bf16x8*)(As + (wm * 128 + i * 16 + l15) * 64 + rsw);
;       __builtin_amdgcn_s_setprio(1);
; #pragma unroll
;       for (int i = 0; i < 8; ++i) {
; #pragma unroll
;         for (int j = 0; j < 4; ++j) acc[i][j] = __builtin_amdgcn_mfma_f32_16x16x32_bf16(bfr[j], afr[i], acc[i][j], 0, 0, 0);
;       }
;       __builtin_amdgcn_s_setprio(0);
;       if (kt + 1 < nk) {
;         char* Aw = smem + (buf ^ 1) * 24576;
;         char* Bw = Aw + 16384;
; #pragma unroll
;         for (int i = 0; i < 4; ++i) *(u32x4*)(Aw + (ldrow + i * 64) * 64 + lsw) = ra[i];
; #pragma unroll
;         for (int i = 0; i < 2; ++i) *(u32x4*)(Bw + (ldrow + i * 64) * 64 + lsw) = rb[i];
;       }
;       __syncthreads();
.LBB0_1303:
	v_add_u32_e32 v153, s29, v151
	v_add3_u32 v186, v153, v148, v149
	v_add_u32_e32 v153, v153, v150
	ds_read_b128 v[174:177], v186 offset:16384
	ds_read_b128 v[178:181], v186 offset:17408
	ds_read_b128 v[182:185], v186 offset:18432
	ds_read_b128 v[186:189], v186 offset:19456
	ds_read_b128 v[190:193], v153
	ds_read_b128 v[194:197], v153 offset:1024
	ds_read_b128 v[198:201], v153 offset:2048
	ds_read_b128 v[210:213], v153 offset:3072
	ds_read_b128 v[220:223], v153 offset:4096
	ds_read_b128 v[224:227], v153 offset:5120
	ds_read_b128 v[230:233], v153 offset:6144
	ds_read_b128 v[234:237], v153 offset:7168
	s_add_i32 s11, s11, 1
	s_setprio 1
	s_waitcnt lgkmcnt(7)
	v_mfma_f32_16x16x32_bf16 v[128:131], v[174:177], v[190:193], v[128:131]
	v_mfma_f32_16x16x32_bf16 v[124:127], v[178:181], v[190:193], v[124:127]
	v_mfma_f32_16x16x32_bf16 v[120:123], v[182:185], v[190:193], v[120:123]
	v_mfma_f32_16x16x32_bf16 v[116:119], v[186:189], v[190:193], v[116:119]
	s_add_u32 s31, s30, s28
	v_lshl_add_u64 v[142:143], v[138:139], 0, s[2:3]
	v_add_co_u32_e32 v154, vcc, s13, v142
	v_lshl_add_u64 v[144:145], v[140:141], 0, s[2:3]
	s_nop 0
	v_addc_co_u32_e32 v155, vcc, 0, v143, vcc
	s_waitcnt lgkmcnt(6)
	v_mfma_f32_16x16x32_bf16 v[112:115], v[174:177], v[194:197], v[112:115]
	v_mfma_f32_16x16x32_bf16 v[108:111], v[178:181], v[194:197], v[108:111]
	v_mfma_f32_16x16x32_bf16 v[104:107], v[182:185], v[194:197], v[104:107]
	v_mfma_f32_16x16x32_bf16 v[100:103], v[186:189], v[194:197], v[100:103]
	v_add_co_u32_e32 v156, vcc, s14, v142
	s_mov_b32 s4, 0x1c80000
	s_nop 0
	v_addc_co_u32_e32 v157, vcc, 0, v143, vcc
	v_add_co_u32_e32 v158, vcc, s15, v142
	s_nop 1
	s_waitcnt lgkmcnt(5)
	v_mfma_f32_16x16x32_bf16 v[96:99], v[174:177], v[198:201], v[96:99]
	v_mfma_f32_16x16x32_bf16 v[92:95], v[178:181], v[198:201], v[92:95]
	v_mfma_f32_16x16x32_bf16 v[88:91], v[182:185], v[198:201], v[88:91]
	v_mfma_f32_16x16x32_bf16 v[84:87], v[186:189], v[198:201], v[84:87]
	v_addc_co_u32_e32 v159, vcc, 0, v143, vcc
	v_add_co_u32_e32 v162, vcc, s16, v142
	s_nop 1
	v_addc_co_u32_e32 v163, vcc, 0, v143, vcc
	v_add_co_u32_e32 v166, vcc, s4, v144
	s_mov_b32 s4, 0x1cc0000
	s_waitcnt lgkmcnt(4)
	v_mfma_f32_16x16x32_bf16 v[80:83], v[174:177], v[210:213], v[80:83]
	v_mfma_f32_16x16x32_bf16 v[76:79], v[178:181], v[210:213], v[76:79]
	v_mfma_f32_16x16x32_bf16 v[72:75], v[182:185], v[210:213], v[72:75]
	v_mfma_f32_16x16x32_bf16 v[68:71], v[186:189], v[210:213], v[68:71]
	s_nop 0
	v_addc_co_u32_e32 v167, vcc, 0, v145, vcc
	v_add_co_u32_e32 v170, vcc, s4, v144
	s_and_b32 s4, s11, 1
	s_nop 0
	v_addc_co_u32_e32 v171, vcc, 0, v145, vcc
	s_waitcnt lgkmcnt(3)
	v_mfma_f32_16x16x32_bf16 v[64:67], v[174:177], v[220:223], v[64:67]
	v_mfma_f32_16x16x32_bf16 v[60:63], v[178:181], v[220:223], v[60:63]
	v_mfma_f32_16x16x32_bf16 v[56:59], v[182:185], v[220:223], v[56:59]
	v_mfma_f32_16x16x32_bf16 v[52:55], v[186:189], v[220:223], v[52:55]
	s_mov_b32 m0, s31
	s_nop 0
	global_load_lds_dwordx4 v[154:155], off
	s_nop 0
	s_add_u32 m0, s31, 0x1000
	s_nop 0
	s_waitcnt lgkmcnt(2)
	v_mfma_f32_16x16x32_bf16 v[48:51], v[174:177], v[224:227], v[48:51]
	v_mfma_f32_16x16x32_bf16 v[44:47], v[178:181], v[224:227], v[44:47]
	v_mfma_f32_16x16x32_bf16 v[40:43], v[182:185], v[224:227], v[40:43]
	v_mfma_f32_16x16x32_bf16 v[36:39], v[186:189], v[224:227], v[36:39]
	global_load_lds_dwordx4 v[156:157], off
	s_nop 0
	s_add_u32 m0, s31, 0x2000
	s_nop 0
	global_load_lds_dwordx4 v[158:159], off
	s_nop 0
	s_waitcnt lgkmcnt(1)
	v_mfma_f32_16x16x32_bf16 v[32:35], v[174:177], v[230:233], v[32:35]
	v_mfma_f32_16x16x32_bf16 v[28:31], v[178:181], v[230:233], v[28:31]
	v_mfma_f32_16x16x32_bf16 v[24:27], v[182:185], v[230:233], v[24:27]
	v_mfma_f32_16x16x32_bf16 v[20:23], v[186:189], v[230:233], v[20:23]
	s_add_u32 m0, s31, 0x3000
	s_nop 0
	global_load_lds_dwordx4 v[162:163], off
	s_nop 0
	s_add_u32 m0, s31, 0x4000
	s_nop 0
	s_waitcnt lgkmcnt(0)
	v_mfma_f32_16x16x32_bf16 v[16:19], v[174:177], v[234:237], v[16:19]
	v_mfma_f32_16x16x32_bf16 v[12:15], v[178:181], v[234:237], v[12:15]
	v_mfma_f32_16x16x32_bf16 v[8:11], v[182:185], v[234:237], v[8:11]
	v_mfma_f32_16x16x32_bf16 v[4:7], v[186:189], v[234:237], v[4:7]
	global_load_lds_dwordx4 v[166:167], off
	s_nop 0
	s_add_u32 m0, s31, 0x5000
	s_nop 0
	global_load_lds_dwordx4 v[170:171], off
	s_setprio 0
	s_add_u32 s2, s2, 64
	s_addc_u32 s3, s3, 0
	s_add_u32 s29, s29, 0x6000
	s_cmp_eq_u32 s29, 0x12000
	s_cselect_b32 s29, 0, s29
	s_add_u32 s30, s30, 0x6000
	s_cmp_eq_u32 s30, 0x12000
	s_cselect_b32 s30, 0, s30
	s_cmp_eq_u32 s12, s2
	s_waitcnt vmcnt(6)
	s_barrier
	s_cbranch_scc0 .LBB0_1303
; DEVI u32 pack2(float a, float b) { return f2bf(a) | (f2bf(b) << 16); }
;     ...
;       const char* As = smem + buf * 24576;
;       const char* Bs = As + 16384;
;       bf16x8 bfr[4];
; #pragma unroll
;       for (int j = 0; j < 4; ++j) bfr[j] = *(const bf16x8*)(Bs + (wn * 64 + j * 16 + l15) * 64 + rsw);
;       bf16x8 afr[8];
; #pragma unroll
;       for (int i = 0; i < 8; ++i) afr[i] = *(const bf16x8*)(As + (wm * 128 + i * 16 + l15) * 64 + rsw);
;       __builtin_amdgcn_s_setprio(1);
; #pragma unroll
;       for (int i = 0; i < 8; ++i) {
; #pragma unroll
;         for (int j = 0; j < 4; ++j) acc[i][j] = __builtin_amdgcn_mfma_f32_16x16x32_bf16(bfr[j], afr[i], acc[i][j], 0, 0, 0);
;       }
;       __builtin_amdgcn_s_setprio(0);
;       if (kt + 1 < nk) {
;         char* Aw = smem + (buf ^ 1) * 24576;
;         char* Bw = Aw + 16384;
; #pragma unroll
;         for (int i = 0; i < 4; ++i) *(u32x4*)(Aw + (ldrow + i * 64) * 64 + lsw) = ra[i];
; #pragma unroll
;         for (int i = 0; i < 2; ++i) *(u32x4*)(Bw + (ldrow + i * 64) * 64 + lsw) = rb[i];
;       }
;       __syncthreads();
;     }
; #pragma unroll
;     for (int i = 0; i < 8; ++i) {
;       const int row = m0 + wm * 128 + i * 16 + l15;
; #pragma unroll
;       for (int j = 0; j < 4; ++j) {
;         const int n = n0 + wn * 64 + j * 16 + quad * 4;
;         f32x4 a = acc[i][j];
;         if (EPI == EPI_Z) {
;           u16* dst;
;           if (n0 < 1536) dst = (u16*)(p.ws + W_ZA) + (size_t)row * LZA + n;
;           else if (n0 < 4736) dst = (u16*)(p.ws + W_ZB) + (size_t)row * LZB + (n - 1536);
;           else dst = (u16*)(p.ws + W_ZC) + (size_t)row * LZC + (n - 4736);
;           *(uint2*)dst = make_uint2(pack2(a[0], a[1]), pack2(a[2], a[3]));
;         } else if (EPI == EPI_RES) {
;           if (split) {
;             float* op = p.out + (size_t)row * D + n;
;             unsafeAtomicAdd(op, a[0]); unsafeAtomicAdd(op + 1, a[1]); unsafeAtomicAdd(op + 2, a[2]); unsafeAtomicAdd(op + 3, a[3]);
;           } else {
;             const float* xin = res_from_input ? xrow_in(p, 0, row) : p.out + (size_t)row * D;
;             float4 xv = *(const float4*)(xin + n);
;             float4 o = make_float4(xv.x + a[0], xv.y + a[1], xv.z + a[2], xv.w + a[3]);
;             *(float4*)(p.out + (size_t)row * D + n) = o;
	v_add_u32_e32 v153, s29, v151
	v_add3_u32 v158, v153, v148, v149
	v_add_u32_e32 v153, v153, v150
	ds_read_b128 v[138:141], v158 offset:16384
	ds_read_b128 v[142:145], v158 offset:17408
	ds_read_b128 v[154:157], v158 offset:18432
	ds_read_b128 v[158:161], v158 offset:19456
	ds_read_b128 v[162:165], v153
	ds_read_b128 v[166:169], v153 offset:1024
	ds_read_b128 v[170:173], v153 offset:2048
	ds_read_b128 v[174:177], v153 offset:3072
	ds_read_b128 v[178:181], v153 offset:4096
	ds_read_b128 v[182:185], v153 offset:5120
	ds_read_b128 v[186:189], v153 offset:6144
	ds_read_b128 v[190:193], v153 offset:7168
	s_setprio 1
	s_waitcnt lgkmcnt(7)
	v_mfma_f32_16x16x32_bf16 v[128:131], v[138:141], v[162:165], v[128:131]
	v_mfma_f32_16x16x32_bf16 v[124:127], v[142:145], v[162:165], v[124:127]
	v_mfma_f32_16x16x32_bf16 v[120:123], v[154:157], v[162:165], v[120:123]
	v_mfma_f32_16x16x32_bf16 v[116:119], v[158:161], v[162:165], v[116:119]
	s_waitcnt lgkmcnt(6)
	v_mfma_f32_16x16x32_bf16 v[112:115], v[138:141], v[166:169], v[112:115]
	v_mfma_f32_16x16x32_bf16 v[108:111], v[142:145], v[166:169], v[108:111]
	v_mfma_f32_16x16x32_bf16 v[104:107], v[154:157], v[166:169], v[104:107]
	v_mfma_f32_16x16x32_bf16 v[100:103], v[158:161], v[166:169], v[100:103]
	s_waitcnt lgkmcnt(5)
	v_mfma_f32_16x16x32_bf16 v[96:99], v[138:141], v[170:173], v[96:99]
	v_mfma_f32_16x16x32_bf16 v[92:95], v[142:145], v[170:173], v[92:95]
	v_mfma_f32_16x16x32_bf16 v[88:91], v[154:157], v[170:173], v[88:91]
	v_mfma_f32_16x16x32_bf16 v[84:87], v[158:161], v[170:173], v[84:87]
	s_waitcnt lgkmcnt(4)
	v_mfma_f32_16x16x32_bf16 v[80:83], v[138:141], v[174:177], v[80:83]
	v_mfma_f32_16x16x32_bf16 v[76:79], v[142:145], v[174:177], v[76:79]
	v_mfma_f32_16x16x32_bf16 v[72:75], v[154:157], v[174:177], v[72:75]
	v_mfma_f32_16x16x32_bf16 v[68:71], v[158:161], v[174:177], v[68:71]
	s_waitcnt lgkmcnt(3)
	v_mfma_f32_16x16x32_bf16 v[64:67], v[138:141], v[178:181], v[64:67]
	v_mfma_f32_16x16x32_bf16 v[60:63], v[142:145], v[178:181], v[60:63]
	v_mfma_f32_16x16x32_bf16 v[56:59], v[154:157], v[178:181], v[56:59]
	v_mfma_f32_16x16x32_bf16 v[52:55], v[158:161], v[178:181], v[52:55]
	s_waitcnt lgkmcnt(2)
	v_mfma_f32_16x16x32_bf16 v[48:51], v[138:141], v[182:185], v[48:51]
	v_mfma_f32_16x16x32_bf16 v[44:47], v[142:145], v[182:185], v[44:47]
	v_mfma_f32_16x16x32_bf16 v[40:43], v[154:157], v[182:185], v[40:43]
	v_mfma_f32_16x16x32_bf16 v[36:39], v[158:161], v[182:185], v[36:39]
	s_waitcnt lgkmcnt(1)
	v_mfma_f32_16x16x32_bf16 v[32:35], v[138:141], v[186:189], v[32:35]
	v_mfma_f32_16x16x32_bf16 v[28:31], v[142:145], v[186:189], v[28:31]
	v_mfma_f32_16x16x32_bf16 v[24:27], v[154:157], v[186:189], v[24:27]
	v_mfma_f32_16x16x32_bf16 v[20:23], v[158:161], v[186:189], v[20:23]
	s_waitcnt lgkmcnt(0)
	v_mfma_f32_16x16x32_bf16 v[16:19], v[138:141], v[190:193], v[16:19]
	v_mfma_f32_16x16x32_bf16 v[12:15], v[142:145], v[190:193], v[12:15]
	v_mfma_f32_16x16x32_bf16 v[8:11], v[154:157], v[190:193], v[8:11]
	v_mfma_f32_16x16x32_bf16 v[4:7], v[158:161], v[190:193], v[4:7]
	s_setprio 0
	s_waitcnt vmcnt(0)
	v_add_u32_e32 v140, s9, v146
	s_mov_b32 s2, 0x8000
	v_ashrrev_i32_e32 v141, 31, v140
	v_add_u32_e32 v139, 0xffff8000, v140
	v_cmp_gt_i32_e64 s[4:5], s2, v140
	v_readlane_b32 s12, v253, 53
	v_or_b32_e32 v138, s10, v147
	v_lshlrev_b64 v[142:143], 13, v[140:141]
	v_cndmask_b32_e64 v145, 0, v141, s[4:5]
	v_cndmask_b32_e64 v144, v139, v140, s[4:5]
	v_readlane_b32 s14, v253, 55
	v_readlane_b32 s15, v253, 56
	v_lshlrev_b64 v[144:145], 13, v[144:145]
	s_mov_b64 s[2:3], -1
	s_and_b64 vcc, exec, s[6:7]
	v_lshl_add_u64 v[142:143], s[14:15], 0, v[142:143]
	v_ashrrev_i32_e32 v139, 31, v138
	s_barrier
	v_readlane_b32 s13, v253, 54
	s_cbranch_vccz .LBB0_1306
	v_readlane_b32 s12, v251, 6
	v_readlane_b32 s13, v251, 7
	v_readlane_b32 s15, v251, 9
	v_readlane_b32 s14, v251, 8
	v_mov_b32_e32 v153, s13
	v_mov_b32_e32 v141, s15
	v_cndmask_b32_e64 v155, v141, v153, s[4:5]
	v_mov_b32_e32 v141, s14
	v_mov_b32_e32 v153, s12
	v_cndmask_b32_e64 v154, v141, v153, s[4:5]
	v_readlane_b32 s2, v254, 7
	v_lshl_add_u64 v[154:155], v[154:155], 0, v[144:145]
	v_readlane_b32 s3, v254, 8
	v_lshlrev_b64 v[158:159], 2, v[138:139]
	v_readlane_b32 s16, v251, 10
	v_cndmask_b32_e64 v155, v143, v155, s[2:3]
	v_cndmask_b32_e64 v154, v142, v154, s[2:3]
	v_lshl_add_u64 v[154:155], v[154:155], 0, v[158:159]
	global_load_dwordx4 v[154:157], v[154:155], off
	v_lshl_add_u64 v[158:159], v[142:143], 0, v[158:159]
	v_readlane_b32 s17, v251, 11
	v_readlane_b32 s18, v251, 12
	v_readlane_b32 s19, v251, 13
	v_readlane_b32 s20, v251, 14
	v_readlane_b32 s21, v251, 15
	v_readlane_b32 s22, v251, 16
	v_readlane_b32 s23, v251, 17
	v_readlane_b32 s24, v251, 18
	v_readlane_b32 s25, v251, 19
	v_readlane_b32 s26, v251, 20
	v_readlane_b32 s27, v251, 21
	s_mov_b64 s[2:3], 0
	s_waitcnt vmcnt(0)
	v_pk_add_f32 v[154:155], v[128:129], v[154:155]
	v_pk_add_f32 v[156:157], v[130:131], v[156:157]
	global_store_dwordx4 v[158:159], v[154:157], off

;     ...
;     for (int kt = 0; kt < nk; ++kt) {
;       const int buf = kt & 1;
;       if (kt + 1 < nk) {
; #pragma unroll
;         for (int i = 0; i < 4; ++i) ra[i] = *(const u32x4*)(Ag + (size_t)(i * 64) * K + (kt + 1) * 32);
; #pragma unroll
;         for (int i = 0; i < 2; ++i) rb[i] = *(const u32x4*)(Bg + (size_t)(i * 64) * K + (kt + 1) * 32);
;       }
;       const char* As = smem + buf * 24576;
;       const char* Bs = As + 16384;
;       bf16x8 bfr[4];
; #pragma unroll
;       for (int j = 0; j < 4; ++j) bfr[j] = *(const bf16x8*)(Bs + (wn * 64 + j * 16 + l15) * 64 + rsw);
;       bf16x8 afr[8];
; #pragma unroll
;       for (int i = 0; i < 8; ++i) afr[i] = *(const bf16x8*)(As + (wm * 128 + i * 16 + l15) * 64 + rsw);
;       __builtin_amdgcn_s_setprio(1);
; #pragma unroll
;       for (int i = 0; i < 8; ++i) {
; #pragma unroll
;         for (int j = 0; j < 4; ++j) acc[i][j] = __builtin_amdgcn_mfma_f32_16x16x32_bf16(bfr[j], afr[i], acc[i][j], 0, 0, 0);
;       }
;       __builtin_amdgcn_s_setprio(0);
;       if (kt + 1 < nk) {
;         char* Aw = smem + (buf ^ 1) * 24576;
;         char* Bw = Aw + 16384;
; #pragma unroll
;         for (int i = 0; i < 4; ++i) *(u32x4*)(Aw + (ldrow + i * 64) * 64 + lsw) = ra[i];
; #pragma unroll
;         for (int i = 0; i < 2; ++i) *(u32x4*)(Bw + (ldrow + i * 64) * 64 + lsw) = rb[i];
;       }
;       __syncthreads();
.LBB0_1459:
	v_add_u32_e32 v174, s21, v147
	v_add3_u32 v186, v174, v144, v145
	v_add_u32_e32 v229, v174, v146
	ds_read_b128 v[174:177], v186 offset:16384
	ds_read_b128 v[178:181], v186 offset:17408
	ds_read_b128 v[182:185], v186 offset:18432
	ds_read_b128 v[186:189], v186 offset:19456
	ds_read_b128 v[190:193], v229
	ds_read_b128 v[194:197], v229 offset:1024
	ds_read_b128 v[198:201], v229 offset:2048
	ds_read_b128 v[210:213], v229 offset:3072
	ds_read_b128 v[220:223], v229 offset:4096
	ds_read_b128 v[224:227], v229 offset:5120
	ds_read_b128 v[230:233], v229 offset:6144
	ds_read_b128 v[234:237], v229 offset:7168
	s_add_i32 s7, s7, 1
	s_setprio 1
	s_waitcnt lgkmcnt(7)
	v_mfma_f32_16x16x32_bf16 v[128:131], v[174:177], v[190:193], v[128:131]
	v_mfma_f32_16x16x32_bf16 v[124:127], v[178:181], v[190:193], v[124:127]
	v_mfma_f32_16x16x32_bf16 v[120:123], v[182:185], v[190:193], v[120:123]
	v_mfma_f32_16x16x32_bf16 v[116:119], v[186:189], v[190:193], v[116:119]
	v_lshl_add_u64 v[150:151], v[140:141], 0, s[2:3]
	v_add_co_u32_e32 v154, vcc, s11, v150
	v_lshl_add_u64 v[152:153], v[138:139], 0, s[2:3]
	s_add_u32 s23, s22, s20
	v_addc_co_u32_e32 v155, vcc, 0, v151, vcc
	s_waitcnt lgkmcnt(6)
	v_mfma_f32_16x16x32_bf16 v[112:115], v[174:177], v[194:197], v[112:115]
	v_mfma_f32_16x16x32_bf16 v[108:111], v[178:181], v[194:197], v[108:111]
	v_mfma_f32_16x16x32_bf16 v[104:107], v[182:185], v[194:197], v[104:107]
	v_mfma_f32_16x16x32_bf16 v[100:103], v[186:189], v[194:197], v[100:103]
	v_add_co_u32_e32 v156, vcc, s12, v150
	s_mov_b32 s8, 0x3de33000
	s_nop 0
	v_addc_co_u32_e32 v157, vcc, 0, v151, vcc
	v_add_co_u32_e32 v158, vcc, s13, v150
	s_waitcnt lgkmcnt(5)
	v_mfma_f32_16x16x32_bf16 v[96:99], v[174:177], v[198:201], v[96:99]
	v_mfma_f32_16x16x32_bf16 v[92:95], v[178:181], v[198:201], v[92:95]
	v_mfma_f32_16x16x32_bf16 v[88:91], v[182:185], v[198:201], v[88:91]
	v_mfma_f32_16x16x32_bf16 v[84:87], v[186:189], v[198:201], v[84:87]
	s_mov_b32 m0, s23
	s_nop 0
	v_addc_co_u32_e32 v159, vcc, 0, v151, vcc
	v_add_co_u32_e32 v162, vcc, s14, v150
	s_nop 1
	s_waitcnt lgkmcnt(4)
	v_mfma_f32_16x16x32_bf16 v[80:83], v[174:177], v[210:213], v[80:83]
	v_mfma_f32_16x16x32_bf16 v[76:79], v[178:181], v[210:213], v[76:79]
	v_mfma_f32_16x16x32_bf16 v[72:75], v[182:185], v[210:213], v[72:75]
	v_mfma_f32_16x16x32_bf16 v[68:71], v[186:189], v[210:213], v[68:71]
	v_addc_co_u32_e32 v163, vcc, 0, v151, vcc
	v_add_co_u32_e32 v166, vcc, s8, v152
	s_mov_b32 s8, 0x3de73000
	s_nop 0
	v_addc_co_u32_e32 v167, vcc, 0, v153, vcc
	s_waitcnt lgkmcnt(3)
	v_mfma_f32_16x16x32_bf16 v[64:67], v[174:177], v[220:223], v[64:67]
	v_mfma_f32_16x16x32_bf16 v[60:63], v[178:181], v[220:223], v[60:63]
	v_mfma_f32_16x16x32_bf16 v[56:59], v[182:185], v[220:223], v[56:59]
	v_mfma_f32_16x16x32_bf16 v[52:55], v[186:189], v[220:223], v[52:55]
	v_add_co_u32_e32 v170, vcc, s8, v152
	s_nop 1
	v_addc_co_u32_e32 v171, vcc, 0, v153, vcc
	global_load_lds_dwordx4 v[154:155], off
	s_add_u32 m0, s23, 0x1000
	s_waitcnt lgkmcnt(2)
	v_mfma_f32_16x16x32_bf16 v[48:51], v[174:177], v[224:227], v[48:51]
	v_mfma_f32_16x16x32_bf16 v[44:47], v[178:181], v[224:227], v[44:47]
	v_mfma_f32_16x16x32_bf16 v[40:43], v[182:185], v[224:227], v[40:43]
	v_mfma_f32_16x16x32_bf16 v[36:39], v[186:189], v[224:227], v[36:39]
	s_nop 0
	global_load_lds_dwordx4 v[156:157], off
	s_add_u32 m0, s23, 0x2000
	s_nop 0
	global_load_lds_dwordx4 v[158:159], off
	s_waitcnt lgkmcnt(1)
	v_mfma_f32_16x16x32_bf16 v[32:35], v[174:177], v[230:233], v[32:35]
	v_mfma_f32_16x16x32_bf16 v[28:31], v[178:181], v[230:233], v[28:31]
	v_mfma_f32_16x16x32_bf16 v[24:27], v[182:185], v[230:233], v[24:27]
	v_mfma_f32_16x16x32_bf16 v[20:23], v[186:189], v[230:233], v[20:23]
	s_add_u32 m0, s23, 0x3000
	s_nop 0
	global_load_lds_dwordx4 v[162:163], off
	s_add_u32 m0, s23, 0x4000
	s_nop 0
	s_waitcnt lgkmcnt(0)
	v_mfma_f32_16x16x32_bf16 v[16:19], v[174:177], v[234:237], v[16:19]
	v_mfma_f32_16x16x32_bf16 v[12:15], v[178:181], v[234:237], v[12:15]
	v_mfma_f32_16x16x32_bf16 v[8:11], v[182:185], v[234:237], v[8:11]
	v_mfma_f32_16x16x32_bf16 v[4:7], v[186:189], v[234:237], v[4:7]
	global_load_lds_dwordx4 v[166:167], off
	s_add_u32 m0, s23, 0x5000
	s_nop 0
	global_load_lds_dwordx4 v[170:171], off
	s_setprio 0
	s_add_u32 s2, s2, 64
	s_addc_u32 s3, s3, 0
	s_add_u32 s21, s21, 0x6000
	s_cmp_eq_u32 s21, 0x12000
	s_cselect_b32 s21, 0, s21
	s_add_u32 s22, s22, 0x6000
	s_cmp_eq_u32 s22, 0x12000
	s_cselect_b32 s22, 0, s22
	s_cmpk_eq_i32 s2, 0x1040
	s_waitcnt vmcnt(6)
	s_barrier
	s_cbranch_scc0 .LBB0_1459
;     ...
;       const char* As = smem + buf * 24576;
;       const char* Bs = As + 16384;
;       bf16x8 bfr[4];
; #pragma unroll
;       for (int j = 0; j < 4; ++j) bfr[j] = *(const bf16x8*)(Bs + (wn * 64 + j * 16 + l15) * 64 + rsw);
;       bf16x8 afr[8];
; #pragma unroll
;       for (int i = 0; i < 8; ++i) afr[i] = *(const bf16x8*)(As + (wm * 128 + i * 16 + l15) * 64 + rsw);
;       __builtin_amdgcn_s_setprio(1);
; #pragma unroll
;       for (int i = 0; i < 8; ++i) {
; #pragma unroll
;         for (int j = 0; j < 4; ++j) acc[i][j] = __builtin_amdgcn_mfma_f32_16x16x32_bf16(bfr[j], afr[i], acc[i][j], 0, 0, 0);
;       }
;       __builtin_amdgcn_s_setprio(0);
;       if (kt + 1 < nk) {
;         char* Aw = smem + (buf ^ 1) * 24576;
;         char* Bw = Aw + 16384;
; #pragma unroll
;         for (int i = 0; i < 4; ++i) *(u32x4*)(Aw + (ldrow + i * 64) * 64 + lsw) = ra[i];
; #pragma unroll
;         for (int i = 0; i < 2; ++i) *(u32x4*)(Bw + (ldrow + i * 64) * 64 + lsw) = rb[i];
;       }
;       __syncthreads();
;     }
; #pragma unroll
;     for (int i = 0; i < 8; ++i) {
;       const int row = m0 + wm * 128 + i * 16 + l15;
; #pragma unroll
;       for (int j = 0; j < 4; ++j) {
;         const int n = n0 + wn * 64 + j * 16 + quad * 4;
;         f32x4 a = acc[i][j];
;         if (EPI == EPI_Z) {
;           u16* dst;
;           if (n0 < 1536) dst = (u16*)(p.ws + W_ZA) + (size_t)row * LZA + n;
;           else if (n0 < 4736) dst = (u16*)(p.ws + W_ZB) + (size_t)row * LZB + (n - 1536);
;           else dst = (u16*)(p.ws + W_ZC) + (size_t)row * LZC + (n - 4736);
;           *(uint2*)dst = make_uint2(pack2(a[0], a[1]), pack2(a[2], a[3]));
;         } else if (EPI == EPI_RES) {
;           if (split) {
;             float* op = p.out + (size_t)row * D + n;
;             unsafeAtomicAdd(op, a[0]); unsafeAtomicAdd(op + 1, a[1]); unsafeAtomicAdd(op + 2, a[2]); unsafeAtomicAdd(op + 3, a[3]);
;           } else {
;             const float* xin = res_from_input ? xrow_in(p, 0, row) : p.out + (size_t)row * D;
;             float4 xv = *(const float4*)(xin + n);
;             float4 o = make_float4(xv.x + a[0], xv.y + a[1], xv.z + a[2], xv.w + a[3]);
;             *(float4*)(p.out + (size_t)row * D + n) = o;
;           }
;         } else {
;           float r0 = fmaxf(a[0], 0.f), r1 = fmaxf(a[1], 0.f), r2 = fmaxf(a[2], 0.f), r3 = fmaxf(a[3], 0.f);
	v_add_u32_e32 v190, s21, v147
	v_add_u32_e32 v194, s21, v149
	v_add_u32_e32 v190, v190, v146
	ds_read_b128 v[138:141], v194 offset:16384
	ds_read_b128 v[150:153], v194 offset:17408
	ds_read_b128 v[154:157], v194 offset:18432
	ds_read_b128 v[158:161], v194 offset:19456
	ds_read_b128 v[162:165], v190
	ds_read_b128 v[166:169], v190 offset:1024
	ds_read_b128 v[170:173], v190 offset:2048
	ds_read_b128 v[174:177], v190 offset:3072
	ds_read_b128 v[178:181], v190 offset:4096
	ds_read_b128 v[182:185], v190 offset:5120
	ds_read_b128 v[186:189], v190 offset:6144
	ds_read_b128 v[190:193], v190 offset:7168
	s_setprio 1
	s_waitcnt lgkmcnt(7)
	v_mfma_f32_16x16x32_bf16 v[128:131], v[138:141], v[162:165], v[128:131]
	v_mfma_f32_16x16x32_bf16 v[124:127], v[150:153], v[162:165], v[124:127]
	v_mfma_f32_16x16x32_bf16 v[120:123], v[154:157], v[162:165], v[120:123]
	v_mfma_f32_16x16x32_bf16 v[116:119], v[158:161], v[162:165], v[116:119]
	s_waitcnt lgkmcnt(6)
	v_mfma_f32_16x16x32_bf16 v[112:115], v[138:141], v[166:169], v[112:115]
	v_mfma_f32_16x16x32_bf16 v[108:111], v[150:153], v[166:169], v[108:111]
	v_mfma_f32_16x16x32_bf16 v[162:165], v[154:157], v[166:169], v[104:107]
	v_mfma_f32_16x16x32_bf16 v[100:103], v[158:161], v[166:169], v[100:103]
	s_waitcnt lgkmcnt(5)
	v_mfma_f32_16x16x32_bf16 v[96:99], v[138:141], v[170:173], v[96:99]
	v_mfma_f32_16x16x32_bf16 v[92:95], v[150:153], v[170:173], v[92:95]
	v_mfma_f32_16x16x32_bf16 v[88:91], v[154:157], v[170:173], v[88:91]
	v_mfma_f32_16x16x32_bf16 v[84:87], v[158:161], v[170:173], v[84:87]
	s_waitcnt lgkmcnt(4)
	v_mfma_f32_16x16x32_bf16 v[80:83], v[138:141], v[174:177], v[80:83]
	v_mfma_f32_16x16x32_bf16 v[76:79], v[150:153], v[174:177], v[76:79]
	v_mfma_f32_16x16x32_bf16 v[72:75], v[154:157], v[174:177], v[72:75]
	v_mfma_f32_16x16x32_bf16 v[68:71], v[158:161], v[174:177], v[68:71]
	s_waitcnt lgkmcnt(3)
	v_mfma_f32_16x16x32_bf16 v[64:67], v[138:141], v[178:181], v[64:67]
	v_mfma_f32_16x16x32_bf16 v[60:63], v[150:153], v[178:181], v[60:63]
	v_mfma_f32_16x16x32_bf16 v[56:59], v[154:157], v[178:181], v[56:59]
	v_mfma_f32_16x16x32_bf16 v[52:55], v[158:161], v[178:181], v[52:55]
	s_waitcnt lgkmcnt(2)
	v_mfma_f32_16x16x32_bf16 v[48:51], v[138:141], v[182:185], v[48:51]
	v_mfma_f32_16x16x32_bf16 v[44:47], v[150:153], v[182:185], v[44:47]
	v_mfma_f32_16x16x32_bf16 v[40:43], v[154:157], v[182:185], v[40:43]
	v_mfma_f32_16x16x32_bf16 v[36:39], v[158:161], v[182:185], v[36:39]
	s_waitcnt lgkmcnt(1)
	v_mfma_f32_16x16x32_bf16 v[32:35], v[138:141], v[186:189], v[32:35]
	v_mfma_f32_16x16x32_bf16 v[28:31], v[150:153], v[186:189], v[28:31]
	v_mfma_f32_16x16x32_bf16 v[24:27], v[154:157], v[186:189], v[24:27]
	v_mfma_f32_16x16x32_bf16 v[20:23], v[158:161], v[186:189], v[20:23]
	s_waitcnt lgkmcnt(0)
	v_mfma_f32_16x16x32_bf16 v[16:19], v[138:141], v[190:193], v[16:19]
	v_mfma_f32_16x16x32_bf16 v[12:15], v[150:153], v[190:193], v[12:15]
	v_mfma_f32_16x16x32_bf16 v[8:11], v[154:157], v[190:193], v[8:11]
	v_mfma_f32_16x16x32_bf16 v[4:7], v[158:161], v[190:193], v[4:7]
	s_setprio 0
	s_waitcnt vmcnt(0)
	v_add_u32_e32 v104, s5, v142
	v_ashrrev_i32_e32 v105, 31, v104
	v_lshlrev_b64 v[138:139], 14, v[104:105]
	v_max_f32_e32 v105, v128, v128
	v_max_f32_e32 v128, 0, v105
	v_max_f32_e32 v105, v129, v129
	v_or_b32_e32 v106, s6, v143
	v_readlane_b32 s2, v251, 60
	v_max_f32_e32 v140, 0, v105
	v_max_f32_e32 v105, v130, v130
	v_readlane_b32 s3, v251, 61
	v_max_f32_e32 v129, 0, v105
	v_max_f32_e32 v105, v131, v131
	v_ashrrev_i32_e32 v107, 31, v106
	v_lshl_add_u64 v[138:139], s[2:3], 0, v[138:139]
	v_max_f32_e32 v141, 0, v105
	v_lshlrev_b64 v[106:107], 1, v[106:107]
	v_pk_mul_f32 v[128:129], v[128:129], v[128:129]
	v_lshl_add_u64 v[130:131], v[138:139], 0, v[106:107]
	v_pk_mul_f32 v[138:139], v[140:141], v[140:141]
	v_and_b32_sdwa v105, v129, v202 dst_sel:DWORD dst_unused:UNUSED_PAD src0_sel:WORD_1 src1_sel:DWORD
	v_and_b32_sdwa v140, v128, v202 dst_sel:DWORD dst_unused:UNUSED_PAD src0_sel:WORD_1 src1_sel:DWORD
	v_add3_u32 v105, v129, v105, s33
	v_and_b32_sdwa v129, v139, v202 dst_sel:DWORD dst_unused:UNUSED_PAD src0_sel:WORD_1 src1_sel:DWORD
	v_add3_u32 v128, v128, v140, s33
	v_and_b32_sdwa v140, v138, v202 dst_sel:DWORD dst_unused:UNUSED_PAD src0_sel:WORD_1 src1_sel:DWORD
	v_add3_u32 v129, v139, v129, s33
	v_add3_u32 v138, v138, v140, s33
	v_and_b32_e32 v129, 0xffff0000, v129
	v_and_b32_e32 v138, 0xffff0000, v138
	v_or_b32_sdwa v129, v129, v105 dst_sel:DWORD dst_unused:UNUSED_PAD src0_sel:DWORD src1_sel:WORD_1
	v_max_f32_e32 v105, v124, v124
	v_or_b32_sdwa v128, v138, v128 dst_sel:DWORD dst_unused:UNUSED_PAD src0_sel:DWORD src1_sel:WORD_1
	v_max_f32_e32 v124, 0, v105
	v_max_f32_e32 v105, v125, v125
	s_barrier
; DEVI u32 pack2(float a, float b) { return f2bf(a) | (f2bf(b) << 16); }
;     ...
; #pragma unroll
;     for (int i = 0; i < 8; ++i) {
;       const int row = m0 + wm * 128 + i * 16 + l15;
; #pragma unroll
;       for (int j = 0; j < 4; ++j) {
;         const int n = n0 + wn * 64 + j * 16 + quad * 4;
;         f32x4 a = acc[i][j];
;         if (EPI == EPI_Z) {
;           u16* dst;
;           if (n0 < 1536) dst = (u16*)(p.ws + W_ZA) + (size_t)row * LZA + n;
;           else if (n0 < 4736) dst = (u16*)(p.ws + W_ZB) + (size_t)row * LZB + (n - 1536);
;           else dst = (u16*)(p.ws + W_ZC) + (size_t)row * LZC + (n - 4736);
;           *(uint2*)dst = make_uint2(pack2(a[0], a[1]), pack2(a[2], a[3]));
;         } else if (EPI == EPI_RES) {
;           if (split) {
;             float* op = p.out + (size_t)row * D + n;
;             unsafeAtomicAdd(op, a[0]); unsafeAtomicAdd(op + 1, a[1]); unsafeAtomicAdd(op + 2, a[2]); unsafeAtomicAdd(op + 3, a[3]);
;           } else {
;             const float* xin = res_from_input ? xrow_in(p, 0, row) : p.out + (size_t)row * D;
;             float4 xv = *(const float4*)(xin + n);
;             float4 o = make_float4(xv.x + a[0], xv.y + a[1], xv.z + a[2], xv.w + a[3]);
;             *(float4*)(p.out + (size_t)row * D + n) = o;
;           }
;         } else {
;           float r0 = fmaxf(a[0], 0.f), r1 = fmaxf(a[1], 0.f), r2 = fmaxf(a[2], 0.f), r3 = fmaxf(a[3], 0.f);
;           u16* dst = (u16*)(p.ws + W_H) + (size_t)row * DFF + n;
;           *(uint2*)dst = make_uint2(pack2(r0 * r0, r1 * r1), pack2(r2 * r2, r3 * r3));
;         }
;       }
;     }
	global_store_dwordx2 v[130:131], v[128:129], off
	v_max_f32_e32 v128, 0, v105
	v_max_f32_e32 v105, v126, v126
	v_max_f32_e32 v125, 0, v105
	v_max_f32_e32 v105, v127, v127
	v_max_f32_e32 v129, 0, v105
	v_pk_mul_f32 v[124:125], v[124:125], v[124:125]
	v_pk_mul_f32 v[126:127], v[128:129], v[128:129]
	v_and_b32_sdwa v105, v125, v202 dst_sel:DWORD dst_unused:UNUSED_PAD src0_sel:WORD_1 src1_sel:DWORD
	v_and_b32_sdwa v128, v124, v202 dst_sel:DWORD dst_unused:UNUSED_PAD src0_sel:WORD_1 src1_sel:DWORD
	v_add3_u32 v105, v125, v105, s33
	v_and_b32_sdwa v125, v127, v202 dst_sel:DWORD dst_unused:UNUSED_PAD src0_sel:WORD_1 src1_sel:DWORD
	v_add3_u32 v124, v124, v128, s33
	v_and_b32_sdwa v128, v126, v202 dst_sel:DWORD dst_unused:UNUSED_PAD src0_sel:WORD_1 src1_sel:DWORD
	v_add3_u32 v125, v127, v125, s33
	v_add3_u32 v126, v126, v128, s33
	v_and_b32_e32 v125, 0xffff0000, v125
	v_and_b32_e32 v126, 0xffff0000, v126
	v_or_b32_sdwa v125, v125, v105 dst_sel:DWORD dst_unused:UNUSED_PAD src0_sel:DWORD src1_sel:WORD_1
	v_max_f32_e32 v105, v120, v120
	v_or_b32_sdwa v124, v126, v124 dst_sel:DWORD dst_unused:UNUSED_PAD src0_sel:DWORD src1_sel:WORD_1
	v_max_f32_e32 v120, 0, v105
	v_max_f32_e32 v105, v121, v121
	global_store_dwordx2 v[130:131], v[124:125], off offset:32
	v_max_f32_e32 v124, 0, v105
	v_max_f32_e32 v105, v122, v122
	v_max_f32_e32 v121, 0, v105
	v_max_f32_e32 v105, v123, v123
	v_max_f32_e32 v125, 0, v105
	v_pk_mul_f32 v[120:121], v[120:121], v[120:121]
	v_pk_mul_f32 v[122:123], v[124:125], v[124:125]
	v_and_b32_sdwa v105, v121, v202 dst_sel:DWORD dst_unused:UNUSED_PAD src0_sel:WORD_1 src1_sel:DWORD
	v_and_b32_sdwa v124, v120, v202 dst_sel:DWORD dst_unused:UNUSED_PAD src0_sel:WORD_1 src1_sel:DWORD
	v_add3_u32 v105, v121, v105, s33
	v_and_b32_sdwa v121, v123, v202 dst_sel:DWORD dst_unused:UNUSED_PAD src0_sel:WORD_1 src1_sel:DWORD
	v_add3_u32 v120, v120, v124, s33
	v_and_b32_sdwa v124, v122, v202 dst_sel:DWORD dst_unused:UNUSED_PAD src0_sel:WORD_1 src1_sel:DWORD
	v_add3_u32 v121, v123, v121, s33
	v_add3_u32 v122, v122, v124, s33
	v_and_b32_e32 v121, 0xffff0000, v121
	v_and_b32_e32 v122, 0xffff0000, v122
	v_or_b32_sdwa v121, v121, v105 dst_sel:DWORD dst_unused:UNUSED_PAD src0_sel:DWORD src1_sel:WORD_1
	v_max_f32_e32 v105, v116, v116
	v_or_b32_sdwa v120, v122, v120 dst_sel:DWORD dst_unused:UNUSED_PAD src0_sel:DWORD src1_sel:WORD_1
	v_max_f32_e32 v116, 0, v105
	v_max_f32_e32 v105, v117, v117
	global_store_dwordx2 v[130:131], v[120:121], off offset:64
	v_max_f32_e32 v120, 0, v105
	v_max_f32_e32 v105, v118, v118
	v_max_f32_e32 v117, 0, v105
	v_max_f32_e32 v105, v119, v119
	v_max_f32_e32 v121, 0, v105
	v_pk_mul_f32 v[116:117], v[116:117], v[116:117]
	v_pk_mul_f32 v[118:119], v[120:121], v[120:121]
	v_and_b32_sdwa v105, v117, v202 dst_sel:DWORD dst_unused:UNUSED_PAD src0_sel:WORD_1 src1_sel:DWORD
	v_and_b32_sdwa v120, v116, v202 dst_sel:DWORD dst_unused:UNUSED_PAD src0_sel:WORD_1 src1_sel:DWORD
	v_add3_u32 v116, v116, v120, s33
	v_add3_u32 v105, v117, v105, s33
	v_and_b32_sdwa v117, v119, v202 dst_sel:DWORD dst_unused:UNUSED_PAD src0_sel:WORD_1 src1_sel:DWORD
	v_and_b32_sdwa v120, v118, v202 dst_sel:DWORD dst_unused:UNUSED_PAD src0_sel:WORD_1 src1_sel:DWORD
	v_add3_u32 v117, v119, v117, s33
	v_add3_u32 v118, v118, v120, s33
	v_and_b32_e32 v117, 0xffff0000, v117
	v_and_b32_e32 v118, 0xffff0000, v118
	v_or_b32_sdwa v117, v117, v105 dst_sel:DWORD dst_unused:UNUSED_PAD src0_sel:DWORD src1_sel:WORD_1
	v_or_b32_sdwa v116, v118, v116 dst_sel:DWORD dst_unused:UNUSED_PAD src0_sel:DWORD src1_sel:WORD_1
	v_max_f32_e32 v105, v112, v112
	global_store_dwordx2 v[130:131], v[116:117], off offset:96
	v_or_b32_e32 v116, 16, v104
	v_max_f32_e32 v112, 0, v105
	v_max_f32_e32 v105, v113, v113
	v_ashrrev_i32_e32 v117, 31, v116
	v_max_f32_e32 v118, 0, v105
	v_max_f32_e32 v105, v114, v114
	v_lshlrev_b64 v[116:117], 14, v[116:117]
	v_max_f32_e32 v113, 0, v105
	v_max_f32_e32 v105, v115, v115
	v_lshl_add_u64 v[116:117], s[2:3], 0, v[116:117]
	v_max_f32_e32 v119, 0, v105
	v_pk_mul_f32 v[112:113], v[112:113], v[112:113]
	v_lshl_add_u64 v[114:115], v[116:117], 0, v[106:107]
	v_pk_mul_f32 v[116:117], v[118:119], v[118:119]
	v_and_b32_sdwa v105, v113, v202 dst_sel:DWORD dst_unused:UNUSED_PAD src0_sel:WORD_1 src1_sel:DWORD
	v_and_b32_sdwa v118, v112, v202 dst_sel:DWORD dst_unused:UNUSED_PAD src0_sel:WORD_1 src1_sel:DWORD
	v_add3_u32 v105, v113, v105, s33
	v_and_b32_sdwa v113, v117, v202 dst_sel:DWORD dst_unused:UNUSED_PAD src0_sel:WORD_1 src1_sel:DWORD
	v_add3_u32 v112, v112, v118, s33
	v_and_b32_sdwa v118, v116, v202 dst_sel:DWORD dst_unused:UNUSED_PAD src0_sel:WORD_1 src1_sel:DWORD
	v_add3_u32 v113, v117, v113, s33
	v_add3_u32 v116, v116, v118, s33
	v_and_b32_e32 v113, 0xffff0000, v113
	v_and_b32_e32 v116, 0xffff0000, v116
	v_or_b32_sdwa v113, v113, v105 dst_sel:DWORD dst_unused:UNUSED_PAD src0_sel:DWORD src1_sel:WORD_1
	v_max_f32_e32 v105, v108, v108
	v_or_b32_sdwa v112, v116, v112 dst_sel:DWORD dst_unused:UNUSED_PAD src0_sel:DWORD src1_sel:WORD_1
	v_max_f32_e32 v108, 0, v105
	v_max_f32_e32 v105, v109, v109
	global_store_dwordx2 v[114:115], v[112:113], off
	v_max_f32_e32 v112, 0, v105
	v_max_f32_e32 v105, v110, v110
	v_max_f32_e32 v109, 0, v105
	v_max_f32_e32 v105, v111, v111
	v_max_f32_e32 v113, 0, v105
	v_pk_mul_f32 v[108:109], v[108:109], v[108:109]
	v_pk_mul_f32 v[110:111], v[112:113], v[112:113]
	v_and_b32_sdwa v105, v109, v202 dst_sel:DWORD dst_unused:UNUSED_PAD src0_sel:WORD_1 src1_sel:DWORD
	v_and_b32_sdwa v112, v108, v202 dst_sel:DWORD dst_unused:UNUSED_PAD src0_sel:WORD_1 src1_sel:DWORD
	v_add3_u32 v108, v108, v112, s33
	v_add3_u32 v105, v109, v105, s33
; DEVI u32 pack2(float a, float b) { return f2bf(a) | (f2bf(b) << 16); }
;     ...
; #pragma unroll
;     for (int i = 0; i < 8; ++i) {
;       const int row = m0 + wm * 128 + i * 16 + l15;
; #pragma unroll
;       for (int j = 0; j < 4; ++j) {
;         const int n = n0 + wn * 64 + j * 16 + quad * 4;
;         f32x4 a = acc[i][j];
;         if (EPI == EPI_Z) {
;           u16* dst;
;           if (n0 < 1536) dst = (u16*)(p.ws + W_ZA) + (size_t)row * LZA + n;
;           else if (n0 < 4736) dst = (u16*)(p.ws + W_ZB) + (size_t)row * LZB + (n - 1536);
;           else dst = (u16*)(p.ws + W_ZC) + (size_t)row * LZC + (n - 4736);
;           *(uint2*)dst = make_uint2(pack2(a[0], a[1]), pack2(a[2], a[3]));
;         } else if (EPI == EPI_RES) {
;           if (split) {
;             float* op = p.out + (size_t)row * D + n;
;             unsafeAtomicAdd(op, a[0]); unsafeAtomicAdd(op + 1, a[1]); unsafeAtomicAdd(op + 2, a[2]); unsafeAtomicAdd(op + 3, a[3]);
;           } else {
;             const float* xin = res_from_input ? xrow_in(p, 0, row) : p.out + (size_t)row * D;
;             float4 xv = *(const float4*)(xin + n);
;             float4 o = make_float4(xv.x + a[0], xv.y + a[1], xv.z + a[2], xv.w + a[3]);
;             *(float4*)(p.out + (size_t)row * D + n) = o;
;           }
;         } else {
;           float r0 = fmaxf(a[0], 0.f), r1 = fmaxf(a[1], 0.f), r2 = fmaxf(a[2], 0.f), r3 = fmaxf(a[3], 0.f);
;           u16* dst = (u16*)(p.ws + W_H) + (size_t)row * DFF + n;
;           *(uint2*)dst = make_uint2(pack2(r0 * r0, r1 * r1), pack2(r2 * r2, r3 * r3));
;         }
;       }
;     }
	v_and_b32_sdwa v109, v111, v202 dst_sel:DWORD dst_unused:UNUSED_PAD src0_sel:WORD_1 src1_sel:DWORD
	v_and_b32_sdwa v112, v110, v202 dst_sel:DWORD dst_unused:UNUSED_PAD src0_sel:WORD_1 src1_sel:DWORD
	v_add3_u32 v109, v111, v109, s33
	v_add3_u32 v110, v110, v112, s33
	v_and_b32_e32 v109, 0xffff0000, v109
	v_and_b32_e32 v110, 0xffff0000, v110
	v_or_b32_sdwa v109, v109, v105 dst_sel:DWORD dst_unused:UNUSED_PAD src0_sel:DWORD src1_sel:WORD_1
	v_or_b32_sdwa v108, v110, v108 dst_sel:DWORD dst_unused:UNUSED_PAD src0_sel:DWORD src1_sel:WORD_1
	v_max_f32_e32 v105, v162, v162
	global_store_dwordx2 v[114:115], v[108:109], off offset:32
	v_max_f32_e32 v108, 0, v105
	v_max_f32_e32 v105, v163, v163
	v_max_f32_e32 v110, 0, v105
	v_max_f32_e32 v105, v164, v164
	v_max_f32_e32 v109, 0, v105
	v_max_f32_e32 v105, v165, v165
	v_max_f32_e32 v111, 0, v105
	v_pk_mul_f32 v[108:109], v[108:109], v[108:109]
	v_pk_mul_f32 v[110:111], v[110:111], v[110:111]
	v_and_b32_sdwa v105, v109, v202 dst_sel:DWORD dst_unused:UNUSED_PAD src0_sel:WORD_1 src1_sel:DWORD
	v_and_b32_sdwa v112, v108, v202 dst_sel:DWORD dst_unused:UNUSED_PAD src0_sel:WORD_1 src1_sel:DWORD
	v_add3_u32 v108, v108, v112, s33
	v_add3_u32 v105, v109, v105, s33
	v_and_b32_sdwa v109, v111, v202 dst_sel:DWORD dst_unused:UNUSED_PAD src0_sel:WORD_1 src1_sel:DWORD
	v_and_b32_sdwa v112, v110, v202 dst_sel:DWORD dst_unused:UNUSED_PAD src0_sel:WORD_1 src1_sel:DWORD
	v_add3_u32 v109, v111, v109, s33
	v_add3_u32 v110, v110, v112, s33
	v_and_b32_e32 v109, 0xffff0000, v109
	v_and_b32_e32 v110, 0xffff0000, v110
	v_or_b32_sdwa v109, v109, v105 dst_sel:DWORD dst_unused:UNUSED_PAD src0_sel:DWORD src1_sel:WORD_1
	v_or_b32_sdwa v108, v110, v108 dst_sel:DWORD dst_unused:UNUSED_PAD src0_sel:DWORD src1_sel:WORD_1
	v_max_f32_e32 v101, v101, v101
	global_store_dwordx2 v[114:115], v[108:109], off offset:64
	v_max_f32_e32 v100, v100, v100
	v_max_f32_e32 v108, 0, v101
	v_max_f32_e32 v101, v102, v102
	v_max_f32_e32 v100, 0, v100
	v_max_f32_e32 v101, 0, v101
	v_max_f32_e32 v102, v103, v103
	v_max_f32_e32 v109, 0, v102
	v_pk_mul_f32 v[100:101], v[100:101], v[100:101]
	v_pk_mul_f32 v[102:103], v[108:109], v[108:109]
	v_and_b32_sdwa v105, v101, v202 dst_sel:DWORD dst_unused:UNUSED_PAD src0_sel:WORD_1 src1_sel:DWORD
	v_and_b32_sdwa v108, v100, v202 dst_sel:DWORD dst_unused:UNUSED_PAD src0_sel:WORD_1 src1_sel:DWORD
	v_add3_u32 v100, v100, v108, s33
	v_add3_u32 v101, v101, v105, s33
	v_and_b32_sdwa v105, v103, v202 dst_sel:DWORD dst_unused:UNUSED_PAD src0_sel:WORD_1 src1_sel:DWORD
	v_and_b32_sdwa v108, v102, v202 dst_sel:DWORD dst_unused:UNUSED_PAD src0_sel:WORD_1 src1_sel:DWORD
	v_add3_u32 v103, v103, v105, s33
	v_add3_u32 v102, v102, v108, s33
	v_and_b32_e32 v103, 0xffff0000, v103
	v_and_b32_e32 v102, 0xffff0000, v102
	v_or_b32_sdwa v101, v103, v101 dst_sel:DWORD dst_unused:UNUSED_PAD src0_sel:DWORD src1_sel:WORD_1
	v_or_b32_sdwa v100, v102, v100 dst_sel:DWORD dst_unused:UNUSED_PAD src0_sel:DWORD src1_sel:WORD_1
	global_store_dwordx2 v[114:115], v[100:101], off offset:96
	v_or_b32_e32 v100, 32, v104
	v_max_f32_e32 v97, v97, v97
	v_ashrrev_i32_e32 v101, 31, v100
	v_max_f32_e32 v96, v96, v96
	v_max_f32_e32 v102, 0, v97
	v_max_f32_e32 v97, v98, v98
	v_lshlrev_b64 v[100:101], 14, v[100:101]
	v_max_f32_e32 v96, 0, v96
	v_max_f32_e32 v97, 0, v97
	v_max_f32_e32 v98, v99, v99
	v_lshl_add_u64 v[100:101], s[2:3], 0, v[100:101]
	v_max_f32_e32 v103, 0, v98
	v_pk_mul_f32 v[96:97], v[96:97], v[96:97]
	v_lshl_add_u64 v[98:99], v[100:101], 0, v[106:107]
	v_pk_mul_f32 v[100:101], v[102:103], v[102:103]
	v_and_b32_sdwa v102, v97, v202 dst_sel:DWORD dst_unused:UNUSED_PAD src0_sel:WORD_1 src1_sel:DWORD
	v_and_b32_sdwa v103, v96, v202 dst_sel:DWORD dst_unused:UNUSED_PAD src0_sel:WORD_1 src1_sel:DWORD
	v_add3_u32 v96, v96, v103, s33
	v_add3_u32 v97, v97, v102, s33
	v_and_b32_sdwa v102, v101, v202 dst_sel:DWORD dst_unused:UNUSED_PAD src0_sel:WORD_1 src1_sel:DWORD
	v_and_b32_sdwa v103, v100, v202 dst_sel:DWORD dst_unused:UNUSED_PAD src0_sel:WORD_1 src1_sel:DWORD
	v_add3_u32 v101, v101, v102, s33
	v_add3_u32 v100, v100, v103, s33
	v_and_b32_e32 v101, 0xffff0000, v101
	v_and_b32_e32 v100, 0xffff0000, v100
	v_or_b32_sdwa v97, v101, v97 dst_sel:DWORD dst_unused:UNUSED_PAD src0_sel:DWORD src1_sel:WORD_1
	v_or_b32_sdwa v96, v100, v96 dst_sel:DWORD dst_unused:UNUSED_PAD src0_sel:DWORD src1_sel:WORD_1
	v_max_f32_e32 v93, v93, v93
	global_store_dwordx2 v[98:99], v[96:97], off
	v_max_f32_e32 v92, v92, v92
	v_max_f32_e32 v96, 0, v93
	v_max_f32_e32 v93, v94, v94
	v_max_f32_e32 v92, 0, v92
	v_max_f32_e32 v93, 0, v93
	v_max_f32_e32 v94, v95, v95
	v_max_f32_e32 v97, 0, v94
	v_pk_mul_f32 v[92:93], v[92:93], v[92:93]
	v_pk_mul_f32 v[94:95], v[96:97], v[96:97]
	v_and_b32_sdwa v96, v93, v202 dst_sel:DWORD dst_unused:UNUSED_PAD src0_sel:WORD_1 src1_sel:DWORD
	v_and_b32_sdwa v97, v92, v202 dst_sel:DWORD dst_unused:UNUSED_PAD src0_sel:WORD_1 src1_sel:DWORD
	v_add3_u32 v92, v92, v97, s33
	v_add3_u32 v93, v93, v96, s33
	v_and_b32_sdwa v96, v95, v202 dst_sel:DWORD dst_unused:UNUSED_PAD src0_sel:WORD_1 src1_sel:DWORD
	v_and_b32_sdwa v97, v94, v202 dst_sel:DWORD dst_unused:UNUSED_PAD src0_sel:WORD_1 src1_sel:DWORD
	v_add3_u32 v95, v95, v96, s33
	v_add3_u32 v94, v94, v97, s33
	v_and_b32_e32 v95, 0xffff0000, v95
	v_and_b32_e32 v94, 0xffff0000, v94
	v_or_b32_sdwa v93, v95, v93 dst_sel:DWORD dst_unused:UNUSED_PAD src0_sel:DWORD src1_sel:WORD_1
	v_or_b32_sdwa v92, v94, v92 dst_sel:DWORD dst_unused:UNUSED_PAD src0_sel:DWORD src1_sel:WORD_1
	v_max_f32_e32 v89, v89, v89
	global_store_dwordx2 v[98:99], v[92:93], off offset:32
	v_max_f32_e32 v88, v88, v88
	v_max_f32_e32 v92, 0, v89
; DEVI u32 pack2(float a, float b) { return f2bf(a) | (f2bf(b) << 16); }
;     ...
; #pragma unroll
;     for (int i = 0; i < 8; ++i) {
;       const int row = m0 + wm * 128 + i * 16 + l15;
; #pragma unroll
;       for (int j = 0; j < 4; ++j) {
;         const int n = n0 + wn * 64 + j * 16 + quad * 4;
;         f32x4 a = acc[i][j];
;         if (EPI == EPI_Z) {
;           u16* dst;
;           if (n0 < 1536) dst = (u16*)(p.ws + W_ZA) + (size_t)row * LZA + n;
;           else if (n0 < 4736) dst = (u16*)(p.ws + W_ZB) + (size_t)row * LZB + (n - 1536);
;           else dst = (u16*)(p.ws + W_ZC) + (size_t)row * LZC + (n - 4736);
;           *(uint2*)dst = make_uint2(pack2(a[0], a[1]), pack2(a[2], a[3]));
;         } else if (EPI == EPI_RES) {
;           if (split) {
;             float* op = p.out + (size_t)row * D + n;
;             unsafeAtomicAdd(op, a[0]); unsafeAtomicAdd(op + 1, a[1]); unsafeAtomicAdd(op + 2, a[2]); unsafeAtomicAdd(op + 3, a[3]);
;           } else {
;             const float* xin = res_from_input ? xrow_in(p, 0, row) : p.out + (size_t)row * D;
;             float4 xv = *(const float4*)(xin + n);
;             float4 o = make_float4(xv.x + a[0], xv.y + a[1], xv.z + a[2], xv.w + a[3]);
;             *(float4*)(p.out + (size_t)row * D + n) = o;
;           }
;         } else {
;           float r0 = fmaxf(a[0], 0.f), r1 = fmaxf(a[1], 0.f), r2 = fmaxf(a[2], 0.f), r3 = fmaxf(a[3], 0.f);
;           u16* dst = (u16*)(p.ws + W_H) + (size_t)row * DFF + n;
;           *(uint2*)dst = make_uint2(pack2(r0 * r0, r1 * r1), pack2(r2 * r2, r3 * r3));
;         }
;       }
;     }
	v_max_f32_e32 v89, v90, v90
	v_max_f32_e32 v88, 0, v88
	v_max_f32_e32 v89, 0, v89
	v_max_f32_e32 v90, v91, v91
	v_max_f32_e32 v93, 0, v90
	v_pk_mul_f32 v[88:89], v[88:89], v[88:89]
	v_pk_mul_f32 v[90:91], v[92:93], v[92:93]
	v_and_b32_sdwa v92, v89, v202 dst_sel:DWORD dst_unused:UNUSED_PAD src0_sel:WORD_1 src1_sel:DWORD
	v_and_b32_sdwa v93, v88, v202 dst_sel:DWORD dst_unused:UNUSED_PAD src0_sel:WORD_1 src1_sel:DWORD
	v_add3_u32 v88, v88, v93, s33
	v_add3_u32 v89, v89, v92, s33
	v_and_b32_sdwa v92, v91, v202 dst_sel:DWORD dst_unused:UNUSED_PAD src0_sel:WORD_1 src1_sel:DWORD
	v_and_b32_sdwa v93, v90, v202 dst_sel:DWORD dst_unused:UNUSED_PAD src0_sel:WORD_1 src1_sel:DWORD
	v_add3_u32 v91, v91, v92, s33
	v_add3_u32 v90, v90, v93, s33
	v_and_b32_e32 v91, 0xffff0000, v91
	v_and_b32_e32 v90, 0xffff0000, v90
	v_or_b32_sdwa v89, v91, v89 dst_sel:DWORD dst_unused:UNUSED_PAD src0_sel:DWORD src1_sel:WORD_1
	v_or_b32_sdwa v88, v90, v88 dst_sel:DWORD dst_unused:UNUSED_PAD src0_sel:DWORD src1_sel:WORD_1
	v_max_f32_e32 v85, v85, v85
	global_store_dwordx2 v[98:99], v[88:89], off offset:64
	v_max_f32_e32 v84, v84, v84
	v_max_f32_e32 v88, 0, v85
	v_max_f32_e32 v85, v86, v86
	v_max_f32_e32 v84, 0, v84
	v_max_f32_e32 v85, 0, v85
	v_max_f32_e32 v86, v87, v87
	v_max_f32_e32 v89, 0, v86
	v_pk_mul_f32 v[84:85], v[84:85], v[84:85]
	v_pk_mul_f32 v[86:87], v[88:89], v[88:89]
	v_and_b32_sdwa v88, v85, v202 dst_sel:DWORD dst_unused:UNUSED_PAD src0_sel:WORD_1 src1_sel:DWORD
	v_and_b32_sdwa v89, v84, v202 dst_sel:DWORD dst_unused:UNUSED_PAD src0_sel:WORD_1 src1_sel:DWORD
	v_add3_u32 v84, v84, v89, s33
	v_add3_u32 v85, v85, v88, s33
	v_and_b32_sdwa v88, v87, v202 dst_sel:DWORD dst_unused:UNUSED_PAD src0_sel:WORD_1 src1_sel:DWORD
	v_and_b32_sdwa v89, v86, v202 dst_sel:DWORD dst_unused:UNUSED_PAD src0_sel:WORD_1 src1_sel:DWORD
	v_add3_u32 v87, v87, v88, s33
	v_add3_u32 v86, v86, v89, s33
	v_and_b32_e32 v87, 0xffff0000, v87
	v_and_b32_e32 v86, 0xffff0000, v86
	v_or_b32_sdwa v85, v87, v85 dst_sel:DWORD dst_unused:UNUSED_PAD src0_sel:DWORD src1_sel:WORD_1
	v_or_b32_sdwa v84, v86, v84 dst_sel:DWORD dst_unused:UNUSED_PAD src0_sel:DWORD src1_sel:WORD_1
	global_store_dwordx2 v[98:99], v[84:85], off offset:96
	v_or_b32_e32 v84, 48, v104
	v_max_f32_e32 v81, v81, v81
	v_ashrrev_i32_e32 v85, 31, v84
	v_max_f32_e32 v80, v80, v80
	v_max_f32_e32 v86, 0, v81
	v_max_f32_e32 v81, v82, v82
	v_lshlrev_b64 v[84:85], 14, v[84:85]
	v_max_f32_e32 v80, 0, v80
	v_max_f32_e32 v81, 0, v81
	v_max_f32_e32 v82, v83, v83
	v_lshl_add_u64 v[84:85], s[2:3], 0, v[84:85]
	v_max_f32_e32 v87, 0, v82
	v_pk_mul_f32 v[80:81], v[80:81], v[80:81]
	v_lshl_add_u64 v[82:83], v[84:85], 0, v[106:107]
	v_pk_mul_f32 v[84:85], v[86:87], v[86:87]
	v_and_b32_sdwa v86, v81, v202 dst_sel:DWORD dst_unused:UNUSED_PAD src0_sel:WORD_1 src1_sel:DWORD
	v_and_b32_sdwa v87, v80, v202 dst_sel:DWORD dst_unused:UNUSED_PAD src0_sel:WORD_1 src1_sel:DWORD
	v_add3_u32 v80, v80, v87, s33
	v_add3_u32 v81, v81, v86, s33
	v_and_b32_sdwa v86, v85, v202 dst_sel:DWORD dst_unused:UNUSED_PAD src0_sel:WORD_1 src1_sel:DWORD
	v_and_b32_sdwa v87, v84, v202 dst_sel:DWORD dst_unused:UNUSED_PAD src0_sel:WORD_1 src1_sel:DWORD
	v_add3_u32 v85, v85, v86, s33
	v_add3_u32 v84, v84, v87, s33
	v_and_b32_e32 v85, 0xffff0000, v85
	v_and_b32_e32 v84, 0xffff0000, v84
	v_or_b32_sdwa v81, v85, v81 dst_sel:DWORD dst_unused:UNUSED_PAD src0_sel:DWORD src1_sel:WORD_1
	v_or_b32_sdwa v80, v84, v80 dst_sel:DWORD dst_unused:UNUSED_PAD src0_sel:DWORD src1_sel:WORD_1
	v_max_f32_e32 v77, v77, v77
	global_store_dwordx2 v[82:83], v[80:81], off
	v_max_f32_e32 v76, v76, v76
	v_max_f32_e32 v80, 0, v77
	v_max_f32_e32 v77, v78, v78
	v_max_f32_e32 v76, 0, v76
	v_max_f32_e32 v77, 0, v77
	v_max_f32_e32 v78, v79, v79
	v_max_f32_e32 v81, 0, v78
	v_pk_mul_f32 v[76:77], v[76:77], v[76:77]
	v_pk_mul_f32 v[78:79], v[80:81], v[80:81]
	v_and_b32_sdwa v80, v77, v202 dst_sel:DWORD dst_unused:UNUSED_PAD src0_sel:WORD_1 src1_sel:DWORD
	v_and_b32_sdwa v81, v76, v202 dst_sel:DWORD dst_unused:UNUSED_PAD src0_sel:WORD_1 src1_sel:DWORD
	v_add3_u32 v76, v76, v81, s33
	v_add3_u32 v77, v77, v80, s33
	v_and_b32_sdwa v80, v79, v202 dst_sel:DWORD dst_unused:UNUSED_PAD src0_sel:WORD_1 src1_sel:DWORD
	v_and_b32_sdwa v81, v78, v202 dst_sel:DWORD dst_unused:UNUSED_PAD src0_sel:WORD_1 src1_sel:DWORD
	v_add3_u32 v79, v79, v80, s33
	v_add3_u32 v78, v78, v81, s33
	v_and_b32_e32 v79, 0xffff0000, v79
	v_and_b32_e32 v78, 0xffff0000, v78
	v_or_b32_sdwa v77, v79, v77 dst_sel:DWORD dst_unused:UNUSED_PAD src0_sel:DWORD src1_sel:WORD_1
	v_or_b32_sdwa v76, v78, v76 dst_sel:DWORD dst_unused:UNUSED_PAD src0_sel:DWORD src1_sel:WORD_1
	v_max_f32_e32 v73, v73, v73
	global_store_dwordx2 v[82:83], v[76:77], off offset:32
	v_max_f32_e32 v72, v72, v72
	v_max_f32_e32 v76, 0, v73
	v_max_f32_e32 v73, v74, v74
	v_max_f32_e32 v72, 0, v72
	v_max_f32_e32 v73, 0, v73
	v_max_f32_e32 v74, v75, v75
	v_max_f32_e32 v77, 0, v74
	v_pk_mul_f32 v[72:73], v[72:73], v[72:73]
	v_pk_mul_f32 v[74:75], v[76:77], v[76:77]
	v_and_b32_sdwa v76, v73, v202 dst_sel:DWORD dst_unused:UNUSED_PAD src0_sel:WORD_1 src1_sel:DWORD
	v_and_b32_sdwa v77, v72, v202 dst_sel:DWORD dst_unused:UNUSED_PAD src0_sel:WORD_1 src1_sel:DWORD
	v_add3_u32 v72, v72, v77, s33
	v_add3_u32 v73, v73, v76, s33
	v_and_b32_sdwa v76, v75, v202 dst_sel:DWORD dst_unused:UNUSED_PAD src0_sel:WORD_1 src1_sel:DWORD
	v_and_b32_sdwa v77, v74, v202 dst_sel:DWORD dst_unused:UNUSED_PAD src0_sel:WORD_1 src1_sel:DWORD
	v_add3_u32 v75, v75, v76, s33
	v_add3_u32 v74, v74, v77, s33
	v_and_b32_e32 v75, 0xffff0000, v75
	v_and_b32_e32 v74, 0xffff0000, v74
	v_or_b32_sdwa v73, v75, v73 dst_sel:DWORD dst_unused:UNUSED_PAD src0_sel:DWORD src1_sel:WORD_1
; DEVI u32 pack2(float a, float b) { return f2bf(a) | (f2bf(b) << 16); }
;     ...
; #pragma unroll
;     for (int i = 0; i < 8; ++i) {
;       const int row = m0 + wm * 128 + i * 16 + l15;
; #pragma unroll
;       for (int j = 0; j < 4; ++j) {
;         const int n = n0 + wn * 64 + j * 16 + quad * 4;
;         f32x4 a = acc[i][j];
;         if (EPI == EPI_Z) {
;           u16* dst;
;           if (n0 < 1536) dst = (u16*)(p.ws + W_ZA) + (size_t)row * LZA + n;
;           else if (n0 < 4736) dst = (u16*)(p.ws + W_ZB) + (size_t)row * LZB + (n - 1536);
;           else dst = (u16*)(p.ws + W_ZC) + (size_t)row * LZC + (n - 4736);
;           *(uint2*)dst = make_uint2(pack2(a[0], a[1]), pack2(a[2], a[3]));
;         } else if (EPI == EPI_RES) {
;           if (split) {
;             float* op = p.out + (size_t)row * D + n;
;             unsafeAtomicAdd(op, a[0]); unsafeAtomicAdd(op + 1, a[1]); unsafeAtomicAdd(op + 2, a[2]); unsafeAtomicAdd(op + 3, a[3]);
;           } else {
;             const float* xin = res_from_input ? xrow_in(p, 0, row) : p.out + (size_t)row * D;
;             float4 xv = *(const float4*)(xin + n);
;             float4 o = make_float4(xv.x + a[0], xv.y + a[1], xv.z + a[2], xv.w + a[3]);
;             *(float4*)(p.out + (size_t)row * D + n) = o;
;           }
;         } else {
;           float r0 = fmaxf(a[0], 0.f), r1 = fmaxf(a[1], 0.f), r2 = fmaxf(a[2], 0.f), r3 = fmaxf(a[3], 0.f);
;           u16* dst = (u16*)(p.ws + W_H) + (size_t)row * DFF + n;
;           *(uint2*)dst = make_uint2(pack2(r0 * r0, r1 * r1), pack2(r2 * r2, r3 * r3));
;         }
;       }
;     }
	v_or_b32_sdwa v72, v74, v72 dst_sel:DWORD dst_unused:UNUSED_PAD src0_sel:DWORD src1_sel:WORD_1
	v_max_f32_e32 v69, v69, v69
	global_store_dwordx2 v[82:83], v[72:73], off offset:64
	v_max_f32_e32 v68, v68, v68
	v_max_f32_e32 v72, 0, v69
	v_max_f32_e32 v69, v70, v70
	v_max_f32_e32 v68, 0, v68
	v_max_f32_e32 v69, 0, v69
	v_max_f32_e32 v70, v71, v71
	v_max_f32_e32 v73, 0, v70
	v_pk_mul_f32 v[68:69], v[68:69], v[68:69]
	v_pk_mul_f32 v[70:71], v[72:73], v[72:73]
	v_and_b32_sdwa v72, v69, v202 dst_sel:DWORD dst_unused:UNUSED_PAD src0_sel:WORD_1 src1_sel:DWORD
	v_and_b32_sdwa v73, v68, v202 dst_sel:DWORD dst_unused:UNUSED_PAD src0_sel:WORD_1 src1_sel:DWORD
	v_add3_u32 v68, v68, v73, s33
	v_add3_u32 v69, v69, v72, s33
	v_and_b32_sdwa v72, v71, v202 dst_sel:DWORD dst_unused:UNUSED_PAD src0_sel:WORD_1 src1_sel:DWORD
	v_and_b32_sdwa v73, v70, v202 dst_sel:DWORD dst_unused:UNUSED_PAD src0_sel:WORD_1 src1_sel:DWORD
	v_add3_u32 v71, v71, v72, s33
	v_add3_u32 v70, v70, v73, s33
	v_and_b32_e32 v71, 0xffff0000, v71
	v_and_b32_e32 v70, 0xffff0000, v70
	v_or_b32_sdwa v69, v71, v69 dst_sel:DWORD dst_unused:UNUSED_PAD src0_sel:DWORD src1_sel:WORD_1
	v_or_b32_sdwa v68, v70, v68 dst_sel:DWORD dst_unused:UNUSED_PAD src0_sel:DWORD src1_sel:WORD_1
	global_store_dwordx2 v[82:83], v[68:69], off offset:96
	v_or_b32_e32 v68, 64, v104
	v_max_f32_e32 v65, v65, v65
	v_ashrrev_i32_e32 v69, 31, v68
	v_max_f32_e32 v64, v64, v64
	v_max_f32_e32 v70, 0, v65
	v_max_f32_e32 v65, v66, v66
	v_lshlrev_b64 v[68:69], 14, v[68:69]
	v_max_f32_e32 v64, 0, v64
	v_max_f32_e32 v65, 0, v65
	v_max_f32_e32 v66, v67, v67
	v_lshl_add_u64 v[68:69], s[2:3], 0, v[68:69]
	v_max_f32_e32 v71, 0, v66
	v_pk_mul_f32 v[64:65], v[64:65], v[64:65]
	v_lshl_add_u64 v[66:67], v[68:69], 0, v[106:107]
	v_pk_mul_f32 v[68:69], v[70:71], v[70:71]
	v_and_b32_sdwa v70, v65, v202 dst_sel:DWORD dst_unused:UNUSED_PAD src0_sel:WORD_1 src1_sel:DWORD
	v_and_b32_sdwa v71, v64, v202 dst_sel:DWORD dst_unused:UNUSED_PAD src0_sel:WORD_1 src1_sel:DWORD
	v_add3_u32 v64, v64, v71, s33
	v_add3_u32 v65, v65, v70, s33
	v_and_b32_sdwa v70, v69, v202 dst_sel:DWORD dst_unused:UNUSED_PAD src0_sel:WORD_1 src1_sel:DWORD
	v_and_b32_sdwa v71, v68, v202 dst_sel:DWORD dst_unused:UNUSED_PAD src0_sel:WORD_1 src1_sel:DWORD
	v_add3_u32 v69, v69, v70, s33
	v_add3_u32 v68, v68, v71, s33
	v_and_b32_e32 v69, 0xffff0000, v69
	v_and_b32_e32 v68, 0xffff0000, v68
	v_or_b32_sdwa v65, v69, v65 dst_sel:DWORD dst_unused:UNUSED_PAD src0_sel:DWORD src1_sel:WORD_1
	v_or_b32_sdwa v64, v68, v64 dst_sel:DWORD dst_unused:UNUSED_PAD src0_sel:DWORD src1_sel:WORD_1
	v_max_f32_e32 v61, v61, v61
	global_store_dwordx2 v[66:67], v[64:65], off
	v_max_f32_e32 v60, v60, v60
	v_max_f32_e32 v64, 0, v61
	v_max_f32_e32 v61, v62, v62
	v_max_f32_e32 v60, 0, v60
	v_max_f32_e32 v61, 0, v61
	v_max_f32_e32 v62, v63, v63
	v_max_f32_e32 v65, 0, v62
	v_pk_mul_f32 v[60:61], v[60:61], v[60:61]
	v_pk_mul_f32 v[62:63], v[64:65], v[64:65]
	v_and_b32_sdwa v64, v61, v202 dst_sel:DWORD dst_unused:UNUSED_PAD src0_sel:WORD_1 src1_sel:DWORD
	v_and_b32_sdwa v65, v60, v202 dst_sel:DWORD dst_unused:UNUSED_PAD src0_sel:WORD_1 src1_sel:DWORD
	v_add3_u32 v60, v60, v65, s33
	v_add3_u32 v61, v61, v64, s33
	v_and_b32_sdwa v64, v63, v202 dst_sel:DWORD dst_unused:UNUSED_PAD src0_sel:WORD_1 src1_sel:DWORD
	v_and_b32_sdwa v65, v62, v202 dst_sel:DWORD dst_unused:UNUSED_PAD src0_sel:WORD_1 src1_sel:DWORD
	v_add3_u32 v63, v63, v64, s33
	v_add3_u32 v62, v62, v65, s33
	v_and_b32_e32 v63, 0xffff0000, v63
	v_and_b32_e32 v62, 0xffff0000, v62
	v_or_b32_sdwa v61, v63, v61 dst_sel:DWORD dst_unused:UNUSED_PAD src0_sel:DWORD src1_sel:WORD_1
	v_or_b32_sdwa v60, v62, v60 dst_sel:DWORD dst_unused:UNUSED_PAD src0_sel:DWORD src1_sel:WORD_1
	v_max_f32_e32 v57, v57, v57
	global_store_dwordx2 v[66:67], v[60:61], off offset:32
	v_max_f32_e32 v56, v56, v56
	v_max_f32_e32 v60, 0, v57
	v_max_f32_e32 v57, v58, v58
	v_max_f32_e32 v56, 0, v56
	v_max_f32_e32 v57, 0, v57
	v_max_f32_e32 v58, v59, v59
	v_max_f32_e32 v61, 0, v58
	v_pk_mul_f32 v[56:57], v[56:57], v[56:57]
	v_pk_mul_f32 v[58:59], v[60:61], v[60:61]
	v_and_b32_sdwa v60, v57, v202 dst_sel:DWORD dst_unused:UNUSED_PAD src0_sel:WORD_1 src1_sel:DWORD
	v_and_b32_sdwa v61, v56, v202 dst_sel:DWORD dst_unused:UNUSED_PAD src0_sel:WORD_1 src1_sel:DWORD
	v_add3_u32 v56, v56, v61, s33
	v_add3_u32 v57, v57, v60, s33
	v_and_b32_sdwa v60, v59, v202 dst_sel:DWORD dst_unused:UNUSED_PAD src0_sel:WORD_1 src1_sel:DWORD
	v_and_b32_sdwa v61, v58, v202 dst_sel:DWORD dst_unused:UNUSED_PAD src0_sel:WORD_1 src1_sel:DWORD
	v_add3_u32 v59, v59, v60, s33
	v_add3_u32 v58, v58, v61, s33
	v_and_b32_e32 v59, 0xffff0000, v59
	v_and_b32_e32 v58, 0xffff0000, v58
	v_or_b32_sdwa v57, v59, v57 dst_sel:DWORD dst_unused:UNUSED_PAD src0_sel:DWORD src1_sel:WORD_1
	v_or_b32_sdwa v56, v58, v56 dst_sel:DWORD dst_unused:UNUSED_PAD src0_sel:DWORD src1_sel:WORD_1
	v_max_f32_e32 v53, v53, v53
	global_store_dwordx2 v[66:67], v[56:57], off offset:64
	v_max_f32_e32 v52, v52, v52
	v_max_f32_e32 v56, 0, v53
	v_max_f32_e32 v53, v54, v54
	v_max_f32_e32 v52, 0, v52
	v_max_f32_e32 v53, 0, v53
	v_max_f32_e32 v54, v55, v55
	v_max_f32_e32 v57, 0, v54
	v_pk_mul_f32 v[52:53], v[52:53], v[52:53]
	v_pk_mul_f32 v[54:55], v[56:57], v[56:57]
	v_and_b32_sdwa v56, v53, v202 dst_sel:DWORD dst_unused:UNUSED_PAD src0_sel:WORD_1 src1_sel:DWORD
	v_and_b32_sdwa v57, v52, v202 dst_sel:DWORD dst_unused:UNUSED_PAD src0_sel:WORD_1 src1_sel:DWORD
	v_add3_u32 v52, v52, v57, s33
	v_add3_u32 v53, v53, v56, s33
	v_and_b32_sdwa v56, v55, v202 dst_sel:DWORD dst_unused:UNUSED_PAD src0_sel:WORD_1 src1_sel:DWORD
	v_and_b32_sdwa v57, v54, v202 dst_sel:DWORD dst_unused:UNUSED_PAD src0_sel:WORD_1 src1_sel:DWORD
; DEVI u32 pack2(float a, float b) { return f2bf(a) | (f2bf(b) << 16); }
;     ...
; #pragma unroll
;     for (int i = 0; i < 8; ++i) {
;       const int row = m0 + wm * 128 + i * 16 + l15;
; #pragma unroll
;       for (int j = 0; j < 4; ++j) {
;         const int n = n0 + wn * 64 + j * 16 + quad * 4;
;         f32x4 a = acc[i][j];
;         if (EPI == EPI_Z) {
;           u16* dst;
;           if (n0 < 1536) dst = (u16*)(p.ws + W_ZA) + (size_t)row * LZA + n;
;           else if (n0 < 4736) dst = (u16*)(p.ws + W_ZB) + (size_t)row * LZB + (n - 1536);
;           else dst = (u16*)(p.ws + W_ZC) + (size_t)row * LZC + (n - 4736);
;           *(uint2*)dst = make_uint2(pack2(a[0], a[1]), pack2(a[2], a[3]));
;         } else if (EPI == EPI_RES) {
;           if (split) {
;             float* op = p.out + (size_t)row * D + n;
;             unsafeAtomicAdd(op, a[0]); unsafeAtomicAdd(op + 1, a[1]); unsafeAtomicAdd(op + 2, a[2]); unsafeAtomicAdd(op + 3, a[3]);
;           } else {
;             const float* xin = res_from_input ? xrow_in(p, 0, row) : p.out + (size_t)row * D;
;             float4 xv = *(const float4*)(xin + n);
;             float4 o = make_float4(xv.x + a[0], xv.y + a[1], xv.z + a[2], xv.w + a[3]);
;             *(float4*)(p.out + (size_t)row * D + n) = o;
;           }
;         } else {
;           float r0 = fmaxf(a[0], 0.f), r1 = fmaxf(a[1], 0.f), r2 = fmaxf(a[2], 0.f), r3 = fmaxf(a[3], 0.f);
;           u16* dst = (u16*)(p.ws + W_H) + (size_t)row * DFF + n;
;           *(uint2*)dst = make_uint2(pack2(r0 * r0, r1 * r1), pack2(r2 * r2, r3 * r3));
;         }
;       }
;     }
	v_add3_u32 v55, v55, v56, s33
	v_add3_u32 v54, v54, v57, s33
	v_and_b32_e32 v55, 0xffff0000, v55
	v_and_b32_e32 v54, 0xffff0000, v54
	v_or_b32_sdwa v53, v55, v53 dst_sel:DWORD dst_unused:UNUSED_PAD src0_sel:DWORD src1_sel:WORD_1
	v_or_b32_sdwa v52, v54, v52 dst_sel:DWORD dst_unused:UNUSED_PAD src0_sel:DWORD src1_sel:WORD_1
	global_store_dwordx2 v[66:67], v[52:53], off offset:96
	v_or_b32_e32 v52, 0x50, v104
	v_max_f32_e32 v49, v49, v49
	v_ashrrev_i32_e32 v53, 31, v52
	v_max_f32_e32 v48, v48, v48
	v_max_f32_e32 v54, 0, v49
	v_max_f32_e32 v49, v50, v50
	v_lshlrev_b64 v[52:53], 14, v[52:53]
	v_max_f32_e32 v48, 0, v48
	v_max_f32_e32 v49, 0, v49
	v_max_f32_e32 v50, v51, v51
	v_lshl_add_u64 v[52:53], s[2:3], 0, v[52:53]
	v_max_f32_e32 v55, 0, v50
	v_pk_mul_f32 v[48:49], v[48:49], v[48:49]
	v_lshl_add_u64 v[50:51], v[52:53], 0, v[106:107]
	v_pk_mul_f32 v[52:53], v[54:55], v[54:55]
	v_and_b32_sdwa v54, v49, v202 dst_sel:DWORD dst_unused:UNUSED_PAD src0_sel:WORD_1 src1_sel:DWORD
	v_and_b32_sdwa v55, v48, v202 dst_sel:DWORD dst_unused:UNUSED_PAD src0_sel:WORD_1 src1_sel:DWORD
	v_add3_u32 v48, v48, v55, s33
	v_add3_u32 v49, v49, v54, s33
	v_and_b32_sdwa v54, v53, v202 dst_sel:DWORD dst_unused:UNUSED_PAD src0_sel:WORD_1 src1_sel:DWORD
	v_and_b32_sdwa v55, v52, v202 dst_sel:DWORD dst_unused:UNUSED_PAD src0_sel:WORD_1 src1_sel:DWORD
	v_add3_u32 v53, v53, v54, s33
	v_add3_u32 v52, v52, v55, s33
	v_and_b32_e32 v53, 0xffff0000, v53
	v_and_b32_e32 v52, 0xffff0000, v52
	v_or_b32_sdwa v49, v53, v49 dst_sel:DWORD dst_unused:UNUSED_PAD src0_sel:DWORD src1_sel:WORD_1
	v_or_b32_sdwa v48, v52, v48 dst_sel:DWORD dst_unused:UNUSED_PAD src0_sel:DWORD src1_sel:WORD_1
	v_max_f32_e32 v45, v45, v45
	global_store_dwordx2 v[50:51], v[48:49], off
	v_max_f32_e32 v44, v44, v44
	v_max_f32_e32 v48, 0, v45
	v_max_f32_e32 v45, v46, v46
	v_max_f32_e32 v44, 0, v44
	v_max_f32_e32 v45, 0, v45
	v_max_f32_e32 v46, v47, v47
	v_max_f32_e32 v49, 0, v46
	v_pk_mul_f32 v[44:45], v[44:45], v[44:45]
	v_pk_mul_f32 v[46:47], v[48:49], v[48:49]
	v_and_b32_sdwa v48, v45, v202 dst_sel:DWORD dst_unused:UNUSED_PAD src0_sel:WORD_1 src1_sel:DWORD
	v_and_b32_sdwa v49, v44, v202 dst_sel:DWORD dst_unused:UNUSED_PAD src0_sel:WORD_1 src1_sel:DWORD
	v_add3_u32 v44, v44, v49, s33
	v_add3_u32 v45, v45, v48, s33
	v_and_b32_sdwa v48, v47, v202 dst_sel:DWORD dst_unused:UNUSED_PAD src0_sel:WORD_1 src1_sel:DWORD
	v_and_b32_sdwa v49, v46, v202 dst_sel:DWORD dst_unused:UNUSED_PAD src0_sel:WORD_1 src1_sel:DWORD
	v_add3_u32 v47, v47, v48, s33
	v_add3_u32 v46, v46, v49, s33
	v_and_b32_e32 v47, 0xffff0000, v47
	v_and_b32_e32 v46, 0xffff0000, v46
	v_or_b32_sdwa v45, v47, v45 dst_sel:DWORD dst_unused:UNUSED_PAD src0_sel:DWORD src1_sel:WORD_1
	v_or_b32_sdwa v44, v46, v44 dst_sel:DWORD dst_unused:UNUSED_PAD src0_sel:DWORD src1_sel:WORD_1
	v_max_f32_e32 v41, v41, v41
	global_store_dwordx2 v[50:51], v[44:45], off offset:32
	v_max_f32_e32 v40, v40, v40
	v_max_f32_e32 v44, 0, v41
	v_max_f32_e32 v41, v42, v42
	v_max_f32_e32 v40, 0, v40
	v_max_f32_e32 v41, 0, v41
	v_max_f32_e32 v42, v43, v43
	v_max_f32_e32 v45, 0, v42
	v_pk_mul_f32 v[40:41], v[40:41], v[40:41]
	v_pk_mul_f32 v[42:43], v[44:45], v[44:45]
	v_and_b32_sdwa v44, v41, v202 dst_sel:DWORD dst_unused:UNUSED_PAD src0_sel:WORD_1 src1_sel:DWORD
	v_and_b32_sdwa v45, v40, v202 dst_sel:DWORD dst_unused:UNUSED_PAD src0_sel:WORD_1 src1_sel:DWORD
	v_add3_u32 v40, v40, v45, s33
	v_add3_u32 v41, v41, v44, s33
	v_and_b32_sdwa v44, v43, v202 dst_sel:DWORD dst_unused:UNUSED_PAD src0_sel:WORD_1 src1_sel:DWORD
	v_and_b32_sdwa v45, v42, v202 dst_sel:DWORD dst_unused:UNUSED_PAD src0_sel:WORD_1 src1_sel:DWORD
	v_add3_u32 v43, v43, v44, s33
	v_add3_u32 v42, v42, v45, s33
	v_and_b32_e32 v43, 0xffff0000, v43
	v_and_b32_e32 v42, 0xffff0000, v42
	v_or_b32_sdwa v41, v43, v41 dst_sel:DWORD dst_unused:UNUSED_PAD src0_sel:DWORD src1_sel:WORD_1
	v_or_b32_sdwa v40, v42, v40 dst_sel:DWORD dst_unused:UNUSED_PAD src0_sel:DWORD src1_sel:WORD_1
	v_max_f32_e32 v37, v37, v37
	global_store_dwordx2 v[50:51], v[40:41], off offset:64
	v_max_f32_e32 v36, v36, v36
	v_max_f32_e32 v40, 0, v37
	v_max_f32_e32 v37, v38, v38
	v_max_f32_e32 v36, 0, v36
	v_max_f32_e32 v37, 0, v37
	v_max_f32_e32 v38, v39, v39
	v_max_f32_e32 v41, 0, v38
	v_pk_mul_f32 v[36:37], v[36:37], v[36:37]
	v_pk_mul_f32 v[38:39], v[40:41], v[40:41]
	v_and_b32_sdwa v40, v37, v202 dst_sel:DWORD dst_unused:UNUSED_PAD src0_sel:WORD_1 src1_sel:DWORD
	v_and_b32_sdwa v41, v36, v202 dst_sel:DWORD dst_unused:UNUSED_PAD src0_sel:WORD_1 src1_sel:DWORD
	v_add3_u32 v36, v36, v41, s33
	v_add3_u32 v37, v37, v40, s33
	v_and_b32_sdwa v40, v39, v202 dst_sel:DWORD dst_unused:UNUSED_PAD src0_sel:WORD_1 src1_sel:DWORD
	v_and_b32_sdwa v41, v38, v202 dst_sel:DWORD dst_unused:UNUSED_PAD src0_sel:WORD_1 src1_sel:DWORD
	v_add3_u32 v39, v39, v40, s33
	v_add3_u32 v38, v38, v41, s33
	v_and_b32_e32 v39, 0xffff0000, v39
	v_and_b32_e32 v38, 0xffff0000, v38
	v_or_b32_sdwa v37, v39, v37 dst_sel:DWORD dst_unused:UNUSED_PAD src0_sel:DWORD src1_sel:WORD_1
	v_or_b32_sdwa v36, v38, v36 dst_sel:DWORD dst_unused:UNUSED_PAD src0_sel:DWORD src1_sel:WORD_1
	global_store_dwordx2 v[50:51], v[36:37], off offset:96
	v_or_b32_e32 v36, 0x60, v104
	v_max_f32_e32 v33, v33, v33
	v_ashrrev_i32_e32 v37, 31, v36
	v_max_f32_e32 v32, v32, v32
	v_max_f32_e32 v38, 0, v33
	v_max_f32_e32 v33, v34, v34
	v_lshlrev_b64 v[36:37], 14, v[36:37]
	v_max_f32_e32 v32, 0, v32
	v_max_f32_e32 v33, 0, v33
	v_max_f32_e32 v34, v35, v35
	v_lshl_add_u64 v[36:37], s[2:3], 0, v[36:37]
	v_max_f32_e32 v39, 0, v34
	v_pk_mul_f32 v[32:33], v[32:33], v[32:33]
	v_lshl_add_u64 v[34:35], v[36:37], 0, v[106:107]
	v_pk_mul_f32 v[36:37], v[38:39], v[38:39]
; DEVI u32 pack2(float a, float b) { return f2bf(a) | (f2bf(b) << 16); }
;     ...
; #pragma unroll
;     for (int i = 0; i < 8; ++i) {
;       const int row = m0 + wm * 128 + i * 16 + l15;
; #pragma unroll
;       for (int j = 0; j < 4; ++j) {
;         const int n = n0 + wn * 64 + j * 16 + quad * 4;
;         f32x4 a = acc[i][j];
;         if (EPI == EPI_Z) {
;           u16* dst;
;           if (n0 < 1536) dst = (u16*)(p.ws + W_ZA) + (size_t)row * LZA + n;
;           else if (n0 < 4736) dst = (u16*)(p.ws + W_ZB) + (size_t)row * LZB + (n - 1536);
;           else dst = (u16*)(p.ws + W_ZC) + (size_t)row * LZC + (n - 4736);
;           *(uint2*)dst = make_uint2(pack2(a[0], a[1]), pack2(a[2], a[3]));
;         } else if (EPI == EPI_RES) {
;           if (split) {
;             float* op = p.out + (size_t)row * D + n;
;             unsafeAtomicAdd(op, a[0]); unsafeAtomicAdd(op + 1, a[1]); unsafeAtomicAdd(op + 2, a[2]); unsafeAtomicAdd(op + 3, a[3]);
;           } else {
;             const float* xin = res_from_input ? xrow_in(p, 0, row) : p.out + (size_t)row * D;
;             float4 xv = *(const float4*)(xin + n);
;             float4 o = make_float4(xv.x + a[0], xv.y + a[1], xv.z + a[2], xv.w + a[3]);
;             *(float4*)(p.out + (size_t)row * D + n) = o;
;           }
;         } else {
;           float r0 = fmaxf(a[0], 0.f), r1 = fmaxf(a[1], 0.f), r2 = fmaxf(a[2], 0.f), r3 = fmaxf(a[3], 0.f);
;           u16* dst = (u16*)(p.ws + W_H) + (size_t)row * DFF + n;
;           *(uint2*)dst = make_uint2(pack2(r0 * r0, r1 * r1), pack2(r2 * r2, r3 * r3));
;         }
;       }
;     }
	v_and_b32_sdwa v38, v33, v202 dst_sel:DWORD dst_unused:UNUSED_PAD src0_sel:WORD_1 src1_sel:DWORD
	v_and_b32_sdwa v39, v32, v202 dst_sel:DWORD dst_unused:UNUSED_PAD src0_sel:WORD_1 src1_sel:DWORD
	v_add3_u32 v32, v32, v39, s33
	v_add3_u32 v33, v33, v38, s33
	v_and_b32_sdwa v38, v37, v202 dst_sel:DWORD dst_unused:UNUSED_PAD src0_sel:WORD_1 src1_sel:DWORD
	v_and_b32_sdwa v39, v36, v202 dst_sel:DWORD dst_unused:UNUSED_PAD src0_sel:WORD_1 src1_sel:DWORD
	v_add3_u32 v37, v37, v38, s33
	v_add3_u32 v36, v36, v39, s33
	v_and_b32_e32 v37, 0xffff0000, v37
	v_and_b32_e32 v36, 0xffff0000, v36
	v_or_b32_sdwa v33, v37, v33 dst_sel:DWORD dst_unused:UNUSED_PAD src0_sel:DWORD src1_sel:WORD_1
	v_or_b32_sdwa v32, v36, v32 dst_sel:DWORD dst_unused:UNUSED_PAD src0_sel:DWORD src1_sel:WORD_1
	v_max_f32_e32 v29, v29, v29
	global_store_dwordx2 v[34:35], v[32:33], off
	v_max_f32_e32 v28, v28, v28
	v_max_f32_e32 v32, 0, v29
	v_max_f32_e32 v29, v30, v30
	v_max_f32_e32 v28, 0, v28
	v_max_f32_e32 v29, 0, v29
	v_max_f32_e32 v30, v31, v31
	v_max_f32_e32 v33, 0, v30
	v_pk_mul_f32 v[28:29], v[28:29], v[28:29]
	v_pk_mul_f32 v[30:31], v[32:33], v[32:33]
	v_and_b32_sdwa v32, v29, v202 dst_sel:DWORD dst_unused:UNUSED_PAD src0_sel:WORD_1 src1_sel:DWORD
	v_and_b32_sdwa v33, v28, v202 dst_sel:DWORD dst_unused:UNUSED_PAD src0_sel:WORD_1 src1_sel:DWORD
	v_add3_u32 v28, v28, v33, s33
	v_add3_u32 v29, v29, v32, s33
	v_and_b32_sdwa v32, v31, v202 dst_sel:DWORD dst_unused:UNUSED_PAD src0_sel:WORD_1 src1_sel:DWORD
	v_and_b32_sdwa v33, v30, v202 dst_sel:DWORD dst_unused:UNUSED_PAD src0_sel:WORD_1 src1_sel:DWORD
	v_add3_u32 v31, v31, v32, s33
	v_add3_u32 v30, v30, v33, s33
	v_and_b32_e32 v31, 0xffff0000, v31
	v_and_b32_e32 v30, 0xffff0000, v30
	v_or_b32_sdwa v29, v31, v29 dst_sel:DWORD dst_unused:UNUSED_PAD src0_sel:DWORD src1_sel:WORD_1
	v_or_b32_sdwa v28, v30, v28 dst_sel:DWORD dst_unused:UNUSED_PAD src0_sel:DWORD src1_sel:WORD_1
	v_max_f32_e32 v25, v25, v25
	global_store_dwordx2 v[34:35], v[28:29], off offset:32
	v_max_f32_e32 v24, v24, v24
	v_max_f32_e32 v28, 0, v25
	v_max_f32_e32 v25, v26, v26
	v_max_f32_e32 v24, 0, v24
	v_max_f32_e32 v25, 0, v25
	v_max_f32_e32 v26, v27, v27
	v_max_f32_e32 v29, 0, v26
	v_pk_mul_f32 v[24:25], v[24:25], v[24:25]
	v_pk_mul_f32 v[26:27], v[28:29], v[28:29]
	v_and_b32_sdwa v28, v25, v202 dst_sel:DWORD dst_unused:UNUSED_PAD src0_sel:WORD_1 src1_sel:DWORD
	v_and_b32_sdwa v29, v24, v202 dst_sel:DWORD dst_unused:UNUSED_PAD src0_sel:WORD_1 src1_sel:DWORD
	v_add3_u32 v24, v24, v29, s33
	v_add3_u32 v25, v25, v28, s33
	v_and_b32_sdwa v28, v27, v202 dst_sel:DWORD dst_unused:UNUSED_PAD src0_sel:WORD_1 src1_sel:DWORD
	v_and_b32_sdwa v29, v26, v202 dst_sel:DWORD dst_unused:UNUSED_PAD src0_sel:WORD_1 src1_sel:DWORD
	v_add3_u32 v27, v27, v28, s33
	v_add3_u32 v26, v26, v29, s33
	v_and_b32_e32 v27, 0xffff0000, v27
	v_and_b32_e32 v26, 0xffff0000, v26
	v_or_b32_sdwa v25, v27, v25 dst_sel:DWORD dst_unused:UNUSED_PAD src0_sel:DWORD src1_sel:WORD_1
	v_or_b32_sdwa v24, v26, v24 dst_sel:DWORD dst_unused:UNUSED_PAD src0_sel:DWORD src1_sel:WORD_1
	v_max_f32_e32 v21, v21, v21
	global_store_dwordx2 v[34:35], v[24:25], off offset:64
	v_max_f32_e32 v20, v20, v20
	v_max_f32_e32 v24, 0, v21
	v_max_f32_e32 v21, v22, v22
	v_max_f32_e32 v20, 0, v20
	v_max_f32_e32 v21, 0, v21
	v_max_f32_e32 v22, v23, v23
	v_max_f32_e32 v25, 0, v22
	v_pk_mul_f32 v[20:21], v[20:21], v[20:21]
	v_pk_mul_f32 v[22:23], v[24:25], v[24:25]
	v_and_b32_sdwa v24, v21, v202 dst_sel:DWORD dst_unused:UNUSED_PAD src0_sel:WORD_1 src1_sel:DWORD
	v_and_b32_sdwa v25, v20, v202 dst_sel:DWORD dst_unused:UNUSED_PAD src0_sel:WORD_1 src1_sel:DWORD
	v_add3_u32 v20, v20, v25, s33
	v_add3_u32 v21, v21, v24, s33
	v_and_b32_sdwa v24, v23, v202 dst_sel:DWORD dst_unused:UNUSED_PAD src0_sel:WORD_1 src1_sel:DWORD
	v_and_b32_sdwa v25, v22, v202 dst_sel:DWORD dst_unused:UNUSED_PAD src0_sel:WORD_1 src1_sel:DWORD
	v_add3_u32 v23, v23, v24, s33
	v_add3_u32 v22, v22, v25, s33
	v_and_b32_e32 v23, 0xffff0000, v23
	v_and_b32_e32 v22, 0xffff0000, v22
	v_or_b32_sdwa v21, v23, v21 dst_sel:DWORD dst_unused:UNUSED_PAD src0_sel:DWORD src1_sel:WORD_1
	v_or_b32_sdwa v20, v22, v20 dst_sel:DWORD dst_unused:UNUSED_PAD src0_sel:DWORD src1_sel:WORD_1
	global_store_dwordx2 v[34:35], v[20:21], off offset:96
	v_or_b32_e32 v20, 0x70, v104
	v_max_f32_e32 v17, v17, v17
	v_ashrrev_i32_e32 v21, 31, v20
	v_max_f32_e32 v16, v16, v16
	v_max_f32_e32 v22, 0, v17
	v_max_f32_e32 v17, v18, v18
	v_lshlrev_b64 v[20:21], 14, v[20:21]
; DEVI u32 pack2(float a, float b) { return f2bf(a) | (f2bf(b) << 16); }
;     ...
; #pragma unroll
;     for (int i = 0; i < 8; ++i) {
;       const int row = m0 + wm * 128 + i * 16 + l15;
; #pragma unroll
;       for (int j = 0; j < 4; ++j) {
;         const int n = n0 + wn * 64 + j * 16 + quad * 4;
;         f32x4 a = acc[i][j];
;         if (EPI == EPI_Z) {
;           u16* dst;
;           if (n0 < 1536) dst = (u16*)(p.ws + W_ZA) + (size_t)row * LZA + n;
;           else if (n0 < 4736) dst = (u16*)(p.ws + W_ZB) + (size_t)row * LZB + (n - 1536);
;           else dst = (u16*)(p.ws + W_ZC) + (size_t)row * LZC + (n - 4736);
;           *(uint2*)dst = make_uint2(pack2(a[0], a[1]), pack2(a[2], a[3]));
;         } else if (EPI == EPI_RES) {
;           if (split) {
;             float* op = p.out + (size_t)row * D + n;
;             unsafeAtomicAdd(op, a[0]); unsafeAtomicAdd(op + 1, a[1]); unsafeAtomicAdd(op + 2, a[2]); unsafeAtomicAdd(op + 3, a[3]);
;           } else {
;             const float* xin = res_from_input ? xrow_in(p, 0, row) : p.out + (size_t)row * D;
;             float4 xv = *(const float4*)(xin + n);
;             float4 o = make_float4(xv.x + a[0], xv.y + a[1], xv.z + a[2], xv.w + a[3]);
;             *(float4*)(p.out + (size_t)row * D + n) = o;
;           }
;         } else {
;           float r0 = fmaxf(a[0], 0.f), r1 = fmaxf(a[1], 0.f), r2 = fmaxf(a[2], 0.f), r3 = fmaxf(a[3], 0.f);
;           u16* dst = (u16*)(p.ws + W_H) + (size_t)row * DFF + n;
;           *(uint2*)dst = make_uint2(pack2(r0 * r0, r1 * r1), pack2(r2 * r2, r3 * r3));
;         }
;       }
;     }
	v_max_f32_e32 v16, 0, v16
	v_max_f32_e32 v17, 0, v17
	v_max_f32_e32 v18, v19, v19
	v_lshl_add_u64 v[20:21], s[2:3], 0, v[20:21]
	v_max_f32_e32 v23, 0, v18
	v_pk_mul_f32 v[16:17], v[16:17], v[16:17]
	v_lshl_add_u64 v[18:19], v[20:21], 0, v[106:107]
	v_pk_mul_f32 v[20:21], v[22:23], v[22:23]
	v_and_b32_sdwa v22, v17, v202 dst_sel:DWORD dst_unused:UNUSED_PAD src0_sel:WORD_1 src1_sel:DWORD
	v_and_b32_sdwa v23, v16, v202 dst_sel:DWORD dst_unused:UNUSED_PAD src0_sel:WORD_1 src1_sel:DWORD
	v_add3_u32 v16, v16, v23, s33
	v_add3_u32 v17, v17, v22, s33
	v_and_b32_sdwa v22, v21, v202 dst_sel:DWORD dst_unused:UNUSED_PAD src0_sel:WORD_1 src1_sel:DWORD
	v_and_b32_sdwa v23, v20, v202 dst_sel:DWORD dst_unused:UNUSED_PAD src0_sel:WORD_1 src1_sel:DWORD
	v_add3_u32 v21, v21, v22, s33
	v_add3_u32 v20, v20, v23, s33
	v_and_b32_e32 v21, 0xffff0000, v21
	v_and_b32_e32 v20, 0xffff0000, v20
	v_or_b32_sdwa v17, v21, v17 dst_sel:DWORD dst_unused:UNUSED_PAD src0_sel:DWORD src1_sel:WORD_1
	v_or_b32_sdwa v16, v20, v16 dst_sel:DWORD dst_unused:UNUSED_PAD src0_sel:DWORD src1_sel:WORD_1
	v_max_f32_e32 v13, v13, v13
	global_store_dwordx2 v[18:19], v[16:17], off
	v_max_f32_e32 v12, v12, v12
	v_max_f32_e32 v16, 0, v13
	v_max_f32_e32 v13, v14, v14
	v_max_f32_e32 v12, 0, v12
	v_max_f32_e32 v13, 0, v13
	v_max_f32_e32 v14, v15, v15
	v_max_f32_e32 v17, 0, v14
	v_pk_mul_f32 v[12:13], v[12:13], v[12:13]
	v_pk_mul_f32 v[14:15], v[16:17], v[16:17]
	v_and_b32_sdwa v16, v13, v202 dst_sel:DWORD dst_unused:UNUSED_PAD src0_sel:WORD_1 src1_sel:DWORD
	v_and_b32_sdwa v17, v12, v202 dst_sel:DWORD dst_unused:UNUSED_PAD src0_sel:WORD_1 src1_sel:DWORD
	v_add3_u32 v12, v12, v17, s33
	v_add3_u32 v13, v13, v16, s33
	v_and_b32_sdwa v16, v15, v202 dst_sel:DWORD dst_unused:UNUSED_PAD src0_sel:WORD_1 src1_sel:DWORD
	v_and_b32_sdwa v17, v14, v202 dst_sel:DWORD dst_unused:UNUSED_PAD src0_sel:WORD_1 src1_sel:DWORD
	v_add3_u32 v15, v15, v16, s33
	v_add3_u32 v14, v14, v17, s33
	v_and_b32_e32 v15, 0xffff0000, v15
	v_and_b32_e32 v14, 0xffff0000, v14
	v_or_b32_sdwa v13, v15, v13 dst_sel:DWORD dst_unused:UNUSED_PAD src0_sel:DWORD src1_sel:WORD_1
	v_or_b32_sdwa v12, v14, v12 dst_sel:DWORD dst_unused:UNUSED_PAD src0_sel:DWORD src1_sel:WORD_1
	v_max_f32_e32 v9, v9, v9
	global_store_dwordx2 v[18:19], v[12:13], off offset:32
	v_max_f32_e32 v8, v8, v8
	v_max_f32_e32 v12, 0, v9
	v_max_f32_e32 v9, v10, v10
	v_max_f32_e32 v8, 0, v8
	v_max_f32_e32 v9, 0, v9
	v_max_f32_e32 v10, v11, v11
	v_max_f32_e32 v13, 0, v10
	v_pk_mul_f32 v[8:9], v[8:9], v[8:9]
	v_pk_mul_f32 v[10:11], v[12:13], v[12:13]
	v_and_b32_sdwa v12, v9, v202 dst_sel:DWORD dst_unused:UNUSED_PAD src0_sel:WORD_1 src1_sel:DWORD
	v_and_b32_sdwa v13, v8, v202 dst_sel:DWORD dst_unused:UNUSED_PAD src0_sel:WORD_1 src1_sel:DWORD
	v_add3_u32 v8, v8, v13, s33
	v_add3_u32 v9, v9, v12, s33
	v_and_b32_sdwa v12, v11, v202 dst_sel:DWORD dst_unused:UNUSED_PAD src0_sel:WORD_1 src1_sel:DWORD
	v_and_b32_sdwa v13, v10, v202 dst_sel:DWORD dst_unused:UNUSED_PAD src0_sel:WORD_1 src1_sel:DWORD
	v_add3_u32 v11, v11, v12, s33
	v_add3_u32 v10, v10, v13, s33
	v_and_b32_e32 v11, 0xffff0000, v11
	v_and_b32_e32 v10, 0xffff0000, v10
	v_or_b32_sdwa v9, v11, v9 dst_sel:DWORD dst_unused:UNUSED_PAD src0_sel:DWORD src1_sel:WORD_1
	v_or_b32_sdwa v8, v10, v8 dst_sel:DWORD dst_unused:UNUSED_PAD src0_sel:DWORD src1_sel:WORD_1
	v_max_f32_e32 v5, v5, v5
	global_store_dwordx2 v[18:19], v[8:9], off offset:64
	v_max_f32_e32 v4, v4, v4
	v_max_f32_e32 v8, 0, v5
	v_max_f32_e32 v5, v6, v6
	v_max_f32_e32 v4, 0, v4
	v_max_f32_e32 v5, 0, v5
	v_max_f32_e32 v6, v7, v7
	v_max_f32_e32 v9, 0, v6
	v_pk_mul_f32 v[4:5], v[4:5], v[4:5]
	v_pk_mul_f32 v[6:7], v[8:9], v[8:9]
	v_and_b32_sdwa v8, v5, v202 dst_sel:DWORD dst_unused:UNUSED_PAD src0_sel:WORD_1 src1_sel:DWORD
	v_and_b32_sdwa v9, v4, v202 dst_sel:DWORD dst_unused:UNUSED_PAD src0_sel:WORD_1 src1_sel:DWORD
	v_add3_u32 v4, v4, v9, s33
	v_add3_u32 v5, v5, v8, s33
	v_and_b32_sdwa v8, v7, v202 dst_sel:DWORD dst_unused:UNUSED_PAD src0_sel:WORD_1 src1_sel:DWORD
	v_and_b32_sdwa v9, v6, v202 dst_sel:DWORD dst_unused:UNUSED_PAD src0_sel:WORD_1 src1_sel:DWORD
	v_add3_u32 v7, v7, v8, s33
	v_add3_u32 v6, v6, v9, s33
	v_and_b32_e32 v7, 0xffff0000, v7
	v_and_b32_e32 v6, 0xffff0000, v6
	v_or_b32_sdwa v5, v7, v5 dst_sel:DWORD dst_unused:UNUSED_PAD src0_sel:DWORD src1_sel:WORD_1
	v_or_b32_sdwa v4, v6, v4 dst_sel:DWORD dst_unused:UNUSED_PAD src0_sel:DWORD src1_sel:WORD_1
	global_store_dwordx2 v[18:19], v[4:5], off offset:96
	s_branch .LBB0_1456

;     ...
;     for (int kt = 0; kt < nk; ++kt) {
;       const int buf = kt & 1;
;       if (kt + 1 < nk) {
; #pragma unroll
;         for (int i = 0; i < 4; ++i) ra[i] = *(const u32x4*)(Ag + (size_t)(i * 64) * K + (kt + 1) * 32);
; #pragma unroll
;         for (int i = 0; i < 2; ++i) rb[i] = *(const u32x4*)(Bg + (size_t)(i * 64) * K + (kt + 1) * 32);
;       }
;       const char* As = smem + buf * 24576;
;       const char* Bs = As + 16384;
;       bf16x8 bfr[4];
; #pragma unroll
;       for (int j = 0; j < 4; ++j) bfr[j] = *(const bf16x8*)(Bs + (wn * 64 + j * 16 + l15) * 64 + rsw);
;       bf16x8 afr[8];
; #pragma unroll
;       for (int i = 0; i < 8; ++i) afr[i] = *(const bf16x8*)(As + (wm * 128 + i * 16 + l15) * 64 + rsw);
;       __builtin_amdgcn_s_setprio(1);
; #pragma unroll
;       for (int i = 0; i < 8; ++i) {
; #pragma unroll
;         for (int j = 0; j < 4; ++j) acc[i][j] = __builtin_amdgcn_mfma_f32_16x16x32_bf16(bfr[j], afr[i], acc[i][j], 0, 0, 0);
;       }
;       __builtin_amdgcn_s_setprio(0);
;       if (kt + 1 < nk) {
;         char* Aw = smem + (buf ^ 1) * 24576;
;         char* Bw = Aw + 16384;
; #pragma unroll
;         for (int i = 0; i < 4; ++i) *(u32x4*)(Aw + (ldrow + i * 64) * 64 + lsw) = ra[i];
; #pragma unroll
;         for (int i = 0; i < 2; ++i) *(u32x4*)(Bw + (ldrow + i * 64) * 64 + lsw) = rb[i];
;       }
;       __syncthreads();
.LBB0_1479:
	v_add_u32_e32 v142, s21, v149
	v_add3_u32 v143, v142, v146, v147
	v_add_u32_e32 v142, v142, v148
	ds_read_b128 v[176:179], v143 offset:16384
	ds_read_b128 v[180:183], v143 offset:17408
	ds_read_b128 v[184:187], v143 offset:18432
	ds_read_b128 v[188:191], v143 offset:19456
	ds_read_b128 v[192:195], v142
	ds_read_b128 v[196:199], v142 offset:1024
	ds_read_b128 v[210:213], v142 offset:2048
	ds_read_b128 v[220:223], v142 offset:3072
	ds_read_b128 v[224:227], v142 offset:4096
	ds_read_b128 v[230:233], v142 offset:5120
	ds_read_b128 v[234:237], v142 offset:6144
	ds_read_b128 v[238:241], v142 offset:7168
	s_add_i32 s11, s11, 1
	s_setprio 1
	s_waitcnt lgkmcnt(7)
	v_mfma_f32_16x16x32_bf16 v[128:131], v[176:179], v[192:195], v[128:131]
	v_mfma_f32_16x16x32_bf16 v[124:127], v[180:183], v[192:195], v[124:127]
	v_mfma_f32_16x16x32_bf16 v[120:123], v[184:187], v[192:195], v[120:123]
	v_mfma_f32_16x16x32_bf16 v[116:119], v[188:191], v[192:195], v[116:119]
	s_add_u32 s23, s22, s20
	v_lshl_add_u64 v[142:143], v[138:139], 0, s[2:3]
	s_mov_b32 s6, 0xa580000
	v_add_co_u32_e32 v154, vcc, s6, v142
	s_mov_b32 s6, 0xa680000
	s_nop 0
	v_addc_co_u32_e32 v155, vcc, 0, v143, vcc
	s_waitcnt lgkmcnt(6)
	v_mfma_f32_16x16x32_bf16 v[112:115], v[176:179], v[196:199], v[112:115]
	v_mfma_f32_16x16x32_bf16 v[108:111], v[180:183], v[196:199], v[108:111]
	v_mfma_f32_16x16x32_bf16 v[104:107], v[184:187], v[196:199], v[104:107]
	v_mfma_f32_16x16x32_bf16 v[100:103], v[188:191], v[196:199], v[100:103]
	v_add_co_u32_e32 v156, vcc, s6, v142
	s_mov_b32 s6, 0xa780000
	s_nop 0
	v_addc_co_u32_e32 v157, vcc, 0, v143, vcc
	v_add_co_u32_e32 v160, vcc, s6, v142
	s_mov_b32 s6, 0xa880000
	s_nop 0
	s_waitcnt lgkmcnt(5)
	v_mfma_f32_16x16x32_bf16 v[96:99], v[176:179], v[210:213], v[96:99]
	v_mfma_f32_16x16x32_bf16 v[92:95], v[180:183], v[210:213], v[92:95]
	v_mfma_f32_16x16x32_bf16 v[88:91], v[184:187], v[210:213], v[88:91]
	v_mfma_f32_16x16x32_bf16 v[84:87], v[188:191], v[210:213], v[84:87]
	v_addc_co_u32_e32 v161, vcc, 0, v143, vcc
	v_add_co_u32_e32 v142, vcc, s6, v142
	v_lshl_add_u64 v[152:153], v[140:141], 0, s[2:3]
	s_nop 0
	v_addc_co_u32_e32 v143, vcc, 0, v143, vcc
	s_mov_b32 s6, 0x338b3000
	v_add_co_u32_e32 v168, vcc, s6, v152
	s_waitcnt lgkmcnt(4)
	v_mfma_f32_16x16x32_bf16 v[80:83], v[176:179], v[220:223], v[80:83]
	v_mfma_f32_16x16x32_bf16 v[76:79], v[180:183], v[220:223], v[76:79]
	v_mfma_f32_16x16x32_bf16 v[72:75], v[184:187], v[220:223], v[72:75]
	v_mfma_f32_16x16x32_bf16 v[68:71], v[188:191], v[220:223], v[68:71]
	s_mov_b32 s6, 0x339b3000
	s_nop 0
	v_addc_co_u32_e32 v169, vcc, 0, v153, vcc
	v_add_co_u32_e32 v172, vcc, s6, v152
	s_and_b32 s6, s11, 1
	s_nop 0
	v_addc_co_u32_e32 v173, vcc, 0, v153, vcc
	s_waitcnt lgkmcnt(3)
	v_mfma_f32_16x16x32_bf16 v[64:67], v[176:179], v[224:227], v[64:67]
	v_mfma_f32_16x16x32_bf16 v[60:63], v[180:183], v[224:227], v[60:63]
	v_mfma_f32_16x16x32_bf16 v[56:59], v[184:187], v[224:227], v[56:59]
	v_mfma_f32_16x16x32_bf16 v[52:55], v[188:191], v[224:227], v[52:55]
	s_mov_b32 m0, s23
	s_nop 0
	global_load_lds_dwordx4 v[154:155], off
	s_nop 0
	s_add_u32 m0, s23, 0x1000
	s_nop 0
	global_load_lds_dwordx4 v[156:157], off
	s_waitcnt lgkmcnt(2)
	v_mfma_f32_16x16x32_bf16 v[48:51], v[176:179], v[230:233], v[48:51]
	v_mfma_f32_16x16x32_bf16 v[44:47], v[180:183], v[230:233], v[44:47]
	v_mfma_f32_16x16x32_bf16 v[40:43], v[184:187], v[230:233], v[40:43]
	v_mfma_f32_16x16x32_bf16 v[36:39], v[188:191], v[230:233], v[36:39]
	s_nop 0
	s_add_u32 m0, s23, 0x2000
	s_nop 0
	global_load_lds_dwordx4 v[160:161], off
	s_nop 0
	s_add_u32 m0, s23, 0x3000
	s_nop 0
	s_waitcnt lgkmcnt(1)
	v_mfma_f32_16x16x32_bf16 v[32:35], v[176:179], v[234:237], v[32:35]
	v_mfma_f32_16x16x32_bf16 v[28:31], v[180:183], v[234:237], v[28:31]
	v_mfma_f32_16x16x32_bf16 v[24:27], v[184:187], v[234:237], v[24:27]
	v_mfma_f32_16x16x32_bf16 v[20:23], v[188:191], v[234:237], v[20:23]
	global_load_lds_dwordx4 v[142:143], off
	s_nop 0
	s_add_u32 m0, s23, 0x4000
	s_nop 0
	global_load_lds_dwordx4 v[168:169], off
	s_nop 0
	s_add_u32 m0, s23, 0x5000
	s_waitcnt lgkmcnt(0)
	v_mfma_f32_16x16x32_bf16 v[16:19], v[176:179], v[238:241], v[16:19]
	v_mfma_f32_16x16x32_bf16 v[12:15], v[180:183], v[238:241], v[12:15]
	v_mfma_f32_16x16x32_bf16 v[8:11], v[184:187], v[238:241], v[8:11]
	v_mfma_f32_16x16x32_bf16 v[4:7], v[188:191], v[238:241], v[4:7]
	s_nop 0
	global_load_lds_dwordx4 v[172:173], off
	s_setprio 0
	s_add_u32 s2, s2, 64
	s_addc_u32 s3, s3, 0
	s_add_u32 s21, s21, 0x6000
	s_cmp_eq_u32 s21, 0x12000
	s_cselect_b32 s21, 0, s21
	s_add_u32 s22, s22, 0x6000
	s_cmp_eq_u32 s22, 0x12000
	s_cselect_b32 s22, 0, s22
	s_cmp_eq_u32 s12, s2
	s_waitcnt vmcnt(6)
	s_barrier
; DEVI u32 pack2(float a, float b) { return f2bf(a) | (f2bf(b) << 16); }
;     ...
;       const char* As = smem + buf * 24576;
;       const char* Bs = As + 16384;
;       bf16x8 bfr[4];
; #pragma unroll
;       for (int j = 0; j < 4; ++j) bfr[j] = *(const bf16x8*)(Bs + (wn * 64 + j * 16 + l15) * 64 + rsw);
;       bf16x8 afr[8];
; #pragma unroll
;       for (int i = 0; i < 8; ++i) afr[i] = *(const bf16x8*)(As + (wm * 128 + i * 16 + l15) * 64 + rsw);
;       __builtin_amdgcn_s_setprio(1);
; #pragma unroll
;       for (int i = 0; i < 8; ++i) {
; #pragma unroll
;         for (int j = 0; j < 4; ++j) acc[i][j] = __builtin_amdgcn_mfma_f32_16x16x32_bf16(bfr[j], afr[i], acc[i][j], 0, 0, 0);
;       }
;       __builtin_amdgcn_s_setprio(0);
;       if (kt + 1 < nk) {
;         char* Aw = smem + (buf ^ 1) * 24576;
;         char* Bw = Aw + 16384;
; #pragma unroll
;         for (int i = 0; i < 4; ++i) *(u32x4*)(Aw + (ldrow + i * 64) * 64 + lsw) = ra[i];
; #pragma unroll
;         for (int i = 0; i < 2; ++i) *(u32x4*)(Bw + (ldrow + i * 64) * 64 + lsw) = rb[i];
;       }
;       __syncthreads();
;     }
; #pragma unroll
;     for (int i = 0; i < 8; ++i) {
;       const int row = m0 + wm * 128 + i * 16 + l15;
; #pragma unroll
;       for (int j = 0; j < 4; ++j) {
;         const int n = n0 + wn * 64 + j * 16 + quad * 4;
;         f32x4 a = acc[i][j];
;         if (EPI == EPI_Z) {
;           u16* dst;
;           if (n0 < 1536) dst = (u16*)(p.ws + W_ZA) + (size_t)row * LZA + n;
;           else if (n0 < 4736) dst = (u16*)(p.ws + W_ZB) + (size_t)row * LZB + (n - 1536);
;           else dst = (u16*)(p.ws + W_ZC) + (size_t)row * LZC + (n - 4736);
;           *(uint2*)dst = make_uint2(pack2(a[0], a[1]), pack2(a[2], a[3]));
;         } else if (EPI == EPI_RES) {
;           if (split) {
;             float* op = p.out + (size_t)row * D + n;
;             unsafeAtomicAdd(op, a[0]); unsafeAtomicAdd(op + 1, a[1]); unsafeAtomicAdd(op + 2, a[2]); unsafeAtomicAdd(op + 3, a[3]);
;           } else {
;             const float* xin = res_from_input ? xrow_in(p, 0, row) : p.out + (size_t)row * D;
;             float4 xv = *(const float4*)(xin + n);
;             float4 o = make_float4(xv.x + a[0], xv.y + a[1], xv.z + a[2], xv.w + a[3]);
;             *(float4*)(p.out + (size_t)row * D + n) = o;
	s_cbranch_scc0 .LBB0_1479
	v_add_u32_e32 v142, s21, v149
	v_add3_u32 v143, v142, v146, v147
	v_add_u32_e32 v142, v142, v148
	ds_read_b128 v[138:141], v143 offset:16384
	ds_read_b128 v[152:155], v143 offset:17408
	ds_read_b128 v[156:159], v143 offset:18432
	ds_read_b128 v[160:163], v143 offset:19456
	ds_read_b128 v[164:167], v142
	ds_read_b128 v[168:171], v142 offset:1024
	ds_read_b128 v[172:175], v142 offset:2048
	ds_read_b128 v[176:179], v142 offset:3072
	ds_read_b128 v[180:183], v142 offset:4096
	ds_read_b128 v[184:187], v142 offset:5120
	ds_read_b128 v[188:191], v142 offset:6144
	ds_read_b128 v[192:195], v142 offset:7168
	s_setprio 1
	s_waitcnt lgkmcnt(7)
	v_mfma_f32_16x16x32_bf16 v[128:131], v[138:141], v[164:167], v[128:131]
	v_mfma_f32_16x16x32_bf16 v[124:127], v[152:155], v[164:167], v[124:127]
	v_mfma_f32_16x16x32_bf16 v[120:123], v[156:159], v[164:167], v[120:123]
	v_mfma_f32_16x16x32_bf16 v[116:119], v[160:163], v[164:167], v[116:119]
	s_waitcnt lgkmcnt(6)
	v_mfma_f32_16x16x32_bf16 v[112:115], v[138:141], v[168:171], v[112:115]
	v_mfma_f32_16x16x32_bf16 v[108:111], v[152:155], v[168:171], v[108:111]
	v_mfma_f32_16x16x32_bf16 v[104:107], v[156:159], v[168:171], v[104:107]
	v_mfma_f32_16x16x32_bf16 v[100:103], v[160:163], v[168:171], v[100:103]
	s_waitcnt lgkmcnt(5)
	v_mfma_f32_16x16x32_bf16 v[96:99], v[138:141], v[172:175], v[96:99]
	v_mfma_f32_16x16x32_bf16 v[92:95], v[152:155], v[172:175], v[92:95]
	v_mfma_f32_16x16x32_bf16 v[88:91], v[156:159], v[172:175], v[88:91]
	v_mfma_f32_16x16x32_bf16 v[84:87], v[160:163], v[172:175], v[84:87]
	s_waitcnt lgkmcnt(4)
	v_mfma_f32_16x16x32_bf16 v[80:83], v[138:141], v[176:179], v[80:83]
	v_mfma_f32_16x16x32_bf16 v[76:79], v[152:155], v[176:179], v[76:79]
	v_mfma_f32_16x16x32_bf16 v[72:75], v[156:159], v[176:179], v[72:75]
	v_mfma_f32_16x16x32_bf16 v[68:71], v[160:163], v[176:179], v[68:71]
	s_waitcnt lgkmcnt(3)
	v_mfma_f32_16x16x32_bf16 v[64:67], v[138:141], v[180:183], v[64:67]
	v_mfma_f32_16x16x32_bf16 v[60:63], v[152:155], v[180:183], v[60:63]
	v_mfma_f32_16x16x32_bf16 v[56:59], v[156:159], v[180:183], v[56:59]
	v_mfma_f32_16x16x32_bf16 v[52:55], v[160:163], v[180:183], v[52:55]
	s_waitcnt lgkmcnt(2)
	v_mfma_f32_16x16x32_bf16 v[48:51], v[138:141], v[184:187], v[48:51]
	v_mfma_f32_16x16x32_bf16 v[44:47], v[152:155], v[184:187], v[44:47]
	v_mfma_f32_16x16x32_bf16 v[40:43], v[156:159], v[184:187], v[40:43]
	v_mfma_f32_16x16x32_bf16 v[36:39], v[160:163], v[184:187], v[36:39]
	s_waitcnt lgkmcnt(1)
	v_mfma_f32_16x16x32_bf16 v[32:35], v[138:141], v[188:191], v[32:35]
	v_mfma_f32_16x16x32_bf16 v[28:31], v[152:155], v[188:191], v[28:31]
	v_mfma_f32_16x16x32_bf16 v[24:27], v[156:159], v[188:191], v[24:27]
	v_mfma_f32_16x16x32_bf16 v[20:23], v[160:163], v[188:191], v[20:23]
	s_waitcnt lgkmcnt(0)
	v_mfma_f32_16x16x32_bf16 v[16:19], v[138:141], v[192:195], v[16:19]
	v_mfma_f32_16x16x32_bf16 v[12:15], v[152:155], v[192:195], v[12:15]
	v_mfma_f32_16x16x32_bf16 v[8:11], v[156:159], v[192:195], v[8:11]
	v_mfma_f32_16x16x32_bf16 v[4:7], v[160:163], v[192:195], v[4:7]
	s_setprio 0
	s_waitcnt vmcnt(0)
	v_add_u32_e32 v140, s9, v144
	v_ashrrev_i32_e32 v141, 31, v140
	v_readlane_b32 s12, v253, 53
	v_or_b32_e32 v138, s10, v145
	v_lshlrev_b64 v[142:143], 13, v[140:141]
	v_readlane_b32 s14, v253, 55
	v_readlane_b32 s15, v253, 56
	v_ashrrev_i32_e32 v139, 31, v138
	s_mov_b64 s[2:3], -1
	v_lshl_add_u64 v[142:143], s[14:15], 0, v[142:143]
	v_lshl_add_u64 v[142:143], v[138:139], 2, v[142:143]
	s_and_b64 vcc, exec, s[4:5]
	s_barrier
	v_readlane_b32 s13, v253, 54
	s_cbranch_vccz .LBB0_1482
	global_load_dwordx4 v[152:155], v[142:143], off
	s_mov_b64 s[2:3], 0
	s_waitcnt vmcnt(0)
	v_pk_add_f32 v[152:153], v[128:129], v[152:153]
	v_pk_add_f32 v[154:155], v[130:131], v[154:155]
	global_store_dwordx4 v[142:143], v[152:155], off
